# P6 out-proj epilogue fused with the following LayerNorm (old phase 7) the same way as phase 9: partial row statistics exchanged among the 4 column-tile workgroups, bf16 rows + (mean,rstd) from the epi
# speedup vs baseline: 1.0930x; 1.0017x over previous
.LBB0_1017:
	v_lshlrev_b32_e32 v130, 3, v152
	v_and_b32_e32 v130, 0x78, v130
	v_ashrrev_i32_e32 v151, 4, v152
	v_lshrrev_b32_e32 v132, 1, v152
	v_and_b32_e32 v191, 0x60, v132
	v_or_b32_e32 v132, 4, v130
	v_lshlrev_b32_e32 v133, 2, v151
	v_bitop3_b32 v134, v133, v130, 48 bitop3:0x6c
	v_bitop3_b32 v133, v133, v132, 48 bitop3:0x6c
	v_lshlrev_b32_e32 v135, 9, v151
	v_lshlrev_b32_e32 v133, 2, v133
	v_add_u32_e32 v150, 32, v151
	v_lshlrev_b32_e32 v134, 2, v134
	v_add3_u32 v147, s77, v133, v135
	v_lshlrev_b32_e32 v133, 2, v150
	v_add3_u32 v146, s77, v134, v135
	v_bitop3_b32 v134, v133, v130, 48 bitop3:0x6c
	v_bitop3_b32 v133, v133, v132, 48 bitop3:0x6c
	v_lshlrev_b32_e32 v135, 9, v150
	v_lshlrev_b32_e32 v133, 2, v133
	v_add_u32_e32 v149, 64, v151
	v_lshlrev_b32_e32 v134, 2, v134
	v_add3_u32 v144, s77, v133, v135
	v_lshlrev_b32_e32 v133, 2, v149
	v_add3_u32 v145, s77, v134, v135
	v_bitop3_b32 v134, v133, v130, 48 bitop3:0x6c
	v_bitop3_b32 v133, v133, v132, 48 bitop3:0x6c
	v_lshlrev_b32_e32 v135, 9, v149
	v_lshlrev_b32_e32 v133, 2, v133
	v_add_u32_e32 v148, 0x60, v151
	v_lshlrev_b32_e32 v134, 2, v134
	v_add3_u32 v142, s77, v133, v135
	v_lshlrev_b32_e32 v133, 2, v148
	v_add3_u32 v143, s77, v134, v135
	v_bitop3_b32 v134, v133, v130, 48 bitop3:0x6c
	v_lshlrev_b32_e32 v134, 2, v134
	v_lshlrev_b32_e32 v135, 9, v148
	v_bitop3_b32 v132, v133, v132, 48 bitop3:0x6c
	s_lshl_b64 s[44:45], s[36:37], 2
	v_add3_u32 v141, s77, v134, v135
	v_lshlrev_b32_e32 v132, 2, v132
	v_add_u32_e32 v134, s38, v151
	s_add_u32 s44, s64, s44
	v_add3_u32 v140, s77, v132, v135
	v_bfe_u32 v190, v152, 4, 2
	v_and_b32_e32 v153, 15, v152
	v_lshlrev_b32_e32 v193, 4, v190
	v_lshlrev_b32_e32 v152, 7, v152
	v_or_b32_e32 v192, v191, v153
	v_bitop3_b32 v153, v191, v193, v153 bitop3:0x36
	v_and_b32_e32 v152, 0xffff8000, v152
	v_lshlrev_b32_e32 v153, 2, v153
	v_lshl_or_b32 v190, v190, 11, v152
	v_add3_u32 v152, s77, v153, v190
	v_bitop3_b32 v149, v192, v193, 16 bitop3:0x36
	v_lshlrev_b32_e32 v149, 2, v149
	v_add3_u32 v149, s77, v149, v190
	v_lshrrev_b32_e32 v227, 4, v0
	v_add_u32_e32 v130, s38, v227
	v_lshlrev_b32_e32 v227, 3, v227
	v_and_b32_e32 v226, 15, v0
	v_lshlrev_b32_e32 v226, 5, v226
	s_lshl_b32 s0, s36, 2
	v_add_u32_e32 v226, s0, v226
	v_mov_b32_e32 v229, 0
	v_mov_b32_e32 v228, v130
	v_lshlrev_b64 v[228:229], 12, v[228:229]
	v_mov_b32_e32 v230, v226
	v_mov_b32_e32 v231, 0
	v_lshl_add_u64 v[228:229], v[228:229], 0, v[230:231]
	v_lshl_add_u64 v[230:231], s[64:65], 0, v[228:229]
	s_mov_b32 s44, 0x20000
	s_mov_b32 s45, 0
	s_mov_b32 s71, 0
	s_nop 1
	s_mov_b32 s70, 0x0
	v_lshl_add_u64 v[150:151], v[230:231], 0, s[70:71]
	v_lshl_add_u64 v[220:221], v[150:151], 0, s[44:45]
	v_lshl_add_u64 v[222:223], v[220:221], 0, s[44:45]
	v_lshl_add_u64 v[224:225], v[222:223], 0, s[44:45]
	global_load_dwordx4 v[186:189], v[150:151], off
	global_load_dwordx4 v[190:193], v[150:151], off offset:16
	global_load_dwordx4 v[194:197], v[220:221], off
	global_load_dwordx4 v[198:201], v[220:221], off offset:16
	global_load_dwordx4 v[202:205], v[222:223], off
	global_load_dwordx4 v[206:209], v[222:223], off offset:16
	global_load_dwordx4 v[210:213], v[224:225], off
	global_load_dwordx4 v[214:217], v[224:225], off offset:16
	ds_write2st64_b32 v152, v126, v127 offset1:2
	ds_write2st64_b32 v152, v128, v129 offset0:4 offset1:6
	ds_write2st64_b32 v149, v98, v99 offset1:2
	ds_write2st64_b32 v149, v100, v101 offset0:4 offset1:6
	ds_write2st64_b32 v152, v102, v103 offset0:32 offset1:34
	ds_write2st64_b32 v152, v104, v105 offset0:36 offset1:38
	ds_write2st64_b32 v149, v106, v107 offset0:32 offset1:34
	ds_write2st64_b32 v149, v108, v109 offset0:36 offset1:38
	ds_write2st64_b32 v152, v110, v111 offset0:64 offset1:66
	ds_write2st64_b32 v152, v112, v113 offset0:68 offset1:70
	ds_write2st64_b32 v149, v114, v115 offset0:64 offset1:66
	ds_write2st64_b32 v149, v116, v117 offset0:68 offset1:70
	ds_write2st64_b32 v152, v118, v119 offset0:96 offset1:98
	ds_write2st64_b32 v152, v120, v121 offset0:100 offset1:102
	ds_write2st64_b32 v149, v122, v123 offset0:96 offset1:98
	ds_write2st64_b32 v149, v124, v125 offset0:100 offset1:102
	s_waitcnt lgkmcnt(0)
	s_barrier
	ds_read_b128 v[154:157], v146
	ds_read_b128 v[158:161], v147
	ds_read_b128 v[162:165], v145
	ds_read_b128 v[166:169], v144
	ds_read_b128 v[170:173], v143
	ds_read_b128 v[174:177], v142
	ds_read_b128 v[178:181], v141
	ds_read_b128 v[182:185], v140
	s_waitcnt vmcnt(0) lgkmcnt(0)
	s_barrier
	v_pk_fma_f32 v[98:99], v[186:187], s[30:31], v[154:155] op_sel_hi:[1,0,1]
	v_pk_fma_f32 v[100:101], v[188:189], s[30:31], v[156:157] op_sel_hi:[1,0,1]
	v_pk_fma_f32 v[102:103], v[190:191], s[30:31], v[158:159] op_sel_hi:[1,0,1]
	v_pk_fma_f32 v[104:105], v[192:193], s[30:31], v[160:161] op_sel_hi:[1,0,1]
	v_pk_fma_f32 v[106:107], v[194:195], s[30:31], v[162:163] op_sel_hi:[1,0,1]
	v_pk_fma_f32 v[108:109], v[196:197], s[30:31], v[164:165] op_sel_hi:[1,0,1]
	v_pk_fma_f32 v[110:111], v[198:199], s[30:31], v[166:167] op_sel_hi:[1,0,1]
	v_pk_fma_f32 v[112:113], v[200:201], s[30:31], v[168:169] op_sel_hi:[1,0,1]
	v_pk_fma_f32 v[114:115], v[202:203], s[30:31], v[170:171] op_sel_hi:[1,0,1]
	v_pk_fma_f32 v[116:117], v[204:205], s[30:31], v[172:173] op_sel_hi:[1,0,1]
	v_pk_fma_f32 v[118:119], v[206:207], s[30:31], v[174:175] op_sel_hi:[1,0,1]
	v_pk_fma_f32 v[120:121], v[208:209], s[30:31], v[176:177] op_sel_hi:[1,0,1]
	v_pk_fma_f32 v[122:123], v[210:211], s[30:31], v[178:179] op_sel_hi:[1,0,1]
	v_pk_fma_f32 v[124:125], v[212:213], s[30:31], v[180:181] op_sel_hi:[1,0,1]
	v_pk_fma_f32 v[126:127], v[214:215], s[30:31], v[182:183] op_sel_hi:[1,0,1]
	v_pk_fma_f32 v[128:129], v[216:217], s[30:31], v[184:185] op_sel_hi:[1,0,1]
	s_mov_b32 s70, 0x200
	v_lshl_add_u64 v[150:151], v[230:231], 0, s[70:71]
	v_lshl_add_u64 v[220:221], v[150:151], 0, s[44:45]
	v_lshl_add_u64 v[222:223], v[220:221], 0, s[44:45]
	v_lshl_add_u64 v[224:225], v[222:223], 0, s[44:45]
	global_load_dwordx4 v[186:189], v[150:151], off
	global_load_dwordx4 v[190:193], v[150:151], off offset:16
	global_load_dwordx4 v[194:197], v[220:221], off
	global_load_dwordx4 v[198:201], v[220:221], off offset:16
	global_load_dwordx4 v[202:205], v[222:223], off
	global_load_dwordx4 v[206:209], v[222:223], off offset:16
	global_load_dwordx4 v[210:213], v[224:225], off
	global_load_dwordx4 v[214:217], v[224:225], off offset:16
	ds_write2st64_b32 v152, v66, v67 offset1:2
	ds_write2st64_b32 v152, v68, v69 offset0:4 offset1:6
	ds_write2st64_b32 v149, v70, v71 offset1:2
	ds_write2st64_b32 v149, v72, v73 offset0:4 offset1:6
	ds_write2st64_b32 v152, v74, v75 offset0:32 offset1:34
	ds_write2st64_b32 v152, v76, v77 offset0:36 offset1:38
	ds_write2st64_b32 v149, v78, v79 offset0:32 offset1:34
	ds_write2st64_b32 v149, v80, v81 offset0:36 offset1:38
	ds_write2st64_b32 v152, v82, v83 offset0:64 offset1:66
	ds_write2st64_b32 v152, v84, v85 offset0:68 offset1:70
	ds_write2st64_b32 v149, v86, v87 offset0:64 offset1:66
	ds_write2st64_b32 v149, v88, v89 offset0:68 offset1:70
	ds_write2st64_b32 v152, v90, v91 offset0:96 offset1:98
	ds_write2st64_b32 v152, v92, v93 offset0:100 offset1:102
	ds_write2st64_b32 v149, v94, v95 offset0:96 offset1:98
	ds_write2st64_b32 v149, v96, v97 offset0:100 offset1:102
	s_waitcnt lgkmcnt(0)
	s_barrier
	ds_read_b128 v[154:157], v146
	ds_read_b128 v[158:161], v147
	ds_read_b128 v[162:165], v145
	ds_read_b128 v[166:169], v144
	ds_read_b128 v[170:173], v143
	ds_read_b128 v[174:177], v142
	ds_read_b128 v[178:181], v141
	ds_read_b128 v[182:185], v140
	s_waitcnt vmcnt(0) lgkmcnt(0)
	s_barrier
	v_pk_fma_f32 v[66:67], v[186:187], s[30:31], v[154:155] op_sel_hi:[1,0,1]
	v_pk_fma_f32 v[68:69], v[188:189], s[30:31], v[156:157] op_sel_hi:[1,0,1]
	v_pk_fma_f32 v[70:71], v[190:191], s[30:31], v[158:159] op_sel_hi:[1,0,1]
	v_pk_fma_f32 v[72:73], v[192:193], s[30:31], v[160:161] op_sel_hi:[1,0,1]
	v_pk_fma_f32 v[74:75], v[194:195], s[30:31], v[162:163] op_sel_hi:[1,0,1]
	v_pk_fma_f32 v[76:77], v[196:197], s[30:31], v[164:165] op_sel_hi:[1,0,1]
	v_pk_fma_f32 v[78:79], v[198:199], s[30:31], v[166:167] op_sel_hi:[1,0,1]
	v_pk_fma_f32 v[80:81], v[200:201], s[30:31], v[168:169] op_sel_hi:[1,0,1]
	v_pk_fma_f32 v[82:83], v[202:203], s[30:31], v[170:171] op_sel_hi:[1,0,1]
	v_pk_fma_f32 v[84:85], v[204:205], s[30:31], v[172:173] op_sel_hi:[1,0,1]
	v_pk_fma_f32 v[86:87], v[206:207], s[30:31], v[174:175] op_sel_hi:[1,0,1]
	v_pk_fma_f32 v[88:89], v[208:209], s[30:31], v[176:177] op_sel_hi:[1,0,1]
	v_pk_fma_f32 v[90:91], v[210:211], s[30:31], v[178:179] op_sel_hi:[1,0,1]
	v_pk_fma_f32 v[92:93], v[212:213], s[30:31], v[180:181] op_sel_hi:[1,0,1]
	v_pk_fma_f32 v[94:95], v[214:215], s[30:31], v[182:183] op_sel_hi:[1,0,1]
	v_pk_fma_f32 v[96:97], v[216:217], s[30:31], v[184:185] op_sel_hi:[1,0,1]
	s_mov_b32 s70, 0x80000
	v_lshl_add_u64 v[150:151], v[230:231], 0, s[70:71]
	v_lshl_add_u64 v[220:221], v[150:151], 0, s[44:45]
	v_lshl_add_u64 v[222:223], v[220:221], 0, s[44:45]
	v_lshl_add_u64 v[224:225], v[222:223], 0, s[44:45]
	global_load_dwordx4 v[186:189], v[150:151], off
	global_load_dwordx4 v[190:193], v[150:151], off offset:16
	global_load_dwordx4 v[194:197], v[220:221], off
	global_load_dwordx4 v[198:201], v[220:221], off offset:16
	global_load_dwordx4 v[202:205], v[222:223], off
	global_load_dwordx4 v[206:209], v[222:223], off offset:16
	global_load_dwordx4 v[210:213], v[224:225], off
	global_load_dwordx4 v[214:217], v[224:225], off offset:16
	ds_write2st64_b32 v152, v34, v35 offset1:2
	ds_write2st64_b32 v152, v36, v37 offset0:4 offset1:6
	ds_write2st64_b32 v149, v38, v39 offset1:2
	ds_write2st64_b32 v149, v40, v41 offset0:4 offset1:6
	ds_write2st64_b32 v152, v42, v43 offset0:32 offset1:34
	ds_write2st64_b32 v152, v44, v45 offset0:36 offset1:38
	ds_write2st64_b32 v149, v46, v47 offset0:32 offset1:34
	ds_write2st64_b32 v149, v48, v49 offset0:36 offset1:38
	ds_write2st64_b32 v152, v50, v51 offset0:64 offset1:66
	ds_write2st64_b32 v152, v52, v53 offset0:68 offset1:70
	ds_write2st64_b32 v149, v54, v55 offset0:64 offset1:66
	ds_write2st64_b32 v149, v56, v57 offset0:68 offset1:70
	ds_write2st64_b32 v152, v58, v59 offset0:96 offset1:98
	ds_write2st64_b32 v152, v60, v61 offset0:100 offset1:102
	ds_write2st64_b32 v149, v62, v63 offset0:96 offset1:98
	ds_write2st64_b32 v149, v64, v65 offset0:100 offset1:102
	s_waitcnt lgkmcnt(0)
	s_barrier
	ds_read_b128 v[154:157], v146
	ds_read_b128 v[158:161], v147
	ds_read_b128 v[162:165], v145
	ds_read_b128 v[166:169], v144
	ds_read_b128 v[170:173], v143
	ds_read_b128 v[174:177], v142
	ds_read_b128 v[178:181], v141
	ds_read_b128 v[182:185], v140
	s_waitcnt vmcnt(0) lgkmcnt(0)
	s_barrier
	v_pk_fma_f32 v[34:35], v[186:187], s[30:31], v[154:155] op_sel_hi:[1,0,1]
	v_pk_fma_f32 v[36:37], v[188:189], s[30:31], v[156:157] op_sel_hi:[1,0,1]
	v_pk_fma_f32 v[38:39], v[190:191], s[30:31], v[158:159] op_sel_hi:[1,0,1]
	v_pk_fma_f32 v[40:41], v[192:193], s[30:31], v[160:161] op_sel_hi:[1,0,1]
	v_pk_fma_f32 v[42:43], v[194:195], s[30:31], v[162:163] op_sel_hi:[1,0,1]
	v_pk_fma_f32 v[44:45], v[196:197], s[30:31], v[164:165] op_sel_hi:[1,0,1]
	v_pk_fma_f32 v[46:47], v[198:199], s[30:31], v[166:167] op_sel_hi:[1,0,1]
	v_pk_fma_f32 v[48:49], v[200:201], s[30:31], v[168:169] op_sel_hi:[1,0,1]
	v_pk_fma_f32 v[50:51], v[202:203], s[30:31], v[170:171] op_sel_hi:[1,0,1]
	v_pk_fma_f32 v[52:53], v[204:205], s[30:31], v[172:173] op_sel_hi:[1,0,1]
	v_pk_fma_f32 v[54:55], v[206:207], s[30:31], v[174:175] op_sel_hi:[1,0,1]
	v_pk_fma_f32 v[56:57], v[208:209], s[30:31], v[176:177] op_sel_hi:[1,0,1]
	v_pk_fma_f32 v[58:59], v[210:211], s[30:31], v[178:179] op_sel_hi:[1,0,1]
	v_pk_fma_f32 v[60:61], v[212:213], s[30:31], v[180:181] op_sel_hi:[1,0,1]
	v_pk_fma_f32 v[62:63], v[214:215], s[30:31], v[182:183] op_sel_hi:[1,0,1]
	v_pk_fma_f32 v[64:65], v[216:217], s[30:31], v[184:185] op_sel_hi:[1,0,1]
	s_mov_b32 s70, 0x80200
	v_lshl_add_u64 v[150:151], v[230:231], 0, s[70:71]
	v_lshl_add_u64 v[220:221], v[150:151], 0, s[44:45]
	v_lshl_add_u64 v[222:223], v[220:221], 0, s[44:45]
	v_lshl_add_u64 v[224:225], v[222:223], 0, s[44:45]
	global_load_dwordx4 v[186:189], v[150:151], off
	global_load_dwordx4 v[190:193], v[150:151], off offset:16
	global_load_dwordx4 v[194:197], v[220:221], off
	global_load_dwordx4 v[198:201], v[220:221], off offset:16
	global_load_dwordx4 v[202:205], v[222:223], off
	global_load_dwordx4 v[206:209], v[222:223], off offset:16
	global_load_dwordx4 v[210:213], v[224:225], off
	global_load_dwordx4 v[214:217], v[224:225], off offset:16
	ds_write2st64_b32 v152, v2, v3 offset1:2
	ds_write2st64_b32 v152, v4, v5 offset0:4 offset1:6
	ds_write2st64_b32 v149, v6, v7 offset1:2
	ds_write2st64_b32 v149, v8, v9 offset0:4 offset1:6
	ds_write2st64_b32 v152, v10, v11 offset0:32 offset1:34
	ds_write2st64_b32 v152, v12, v13 offset0:36 offset1:38
	ds_write2st64_b32 v149, v14, v15 offset0:32 offset1:34
	ds_write2st64_b32 v149, v16, v17 offset0:36 offset1:38
	ds_write2st64_b32 v152, v18, v19 offset0:64 offset1:66
	ds_write2st64_b32 v152, v20, v21 offset0:68 offset1:70
	ds_write2st64_b32 v149, v22, v23 offset0:64 offset1:66
	ds_write2st64_b32 v149, v24, v25 offset0:68 offset1:70
	ds_write2st64_b32 v152, v26, v27 offset0:96 offset1:98
	ds_write2st64_b32 v152, v28, v29 offset0:100 offset1:102
	ds_write2st64_b32 v149, v30, v31 offset0:96 offset1:98
	ds_write2st64_b32 v149, v32, v33 offset0:100 offset1:102
	s_waitcnt lgkmcnt(0)
	s_barrier
	ds_read_b128 v[154:157], v146
	ds_read_b128 v[158:161], v147
	ds_read_b128 v[162:165], v145
	ds_read_b128 v[166:169], v144
	ds_read_b128 v[170:173], v143
	ds_read_b128 v[174:177], v142
	ds_read_b128 v[178:181], v141
	ds_read_b128 v[182:185], v140
	s_waitcnt vmcnt(0) lgkmcnt(0)
	v_pk_fma_f32 v[2:3], v[186:187], s[30:31], v[154:155] op_sel_hi:[1,0,1]
	v_pk_fma_f32 v[4:5], v[188:189], s[30:31], v[156:157] op_sel_hi:[1,0,1]
	v_pk_fma_f32 v[6:7], v[190:191], s[30:31], v[158:159] op_sel_hi:[1,0,1]
	v_pk_fma_f32 v[8:9], v[192:193], s[30:31], v[160:161] op_sel_hi:[1,0,1]
	v_pk_fma_f32 v[10:11], v[194:195], s[30:31], v[162:163] op_sel_hi:[1,0,1]
	v_pk_fma_f32 v[12:13], v[196:197], s[30:31], v[164:165] op_sel_hi:[1,0,1]
	v_pk_fma_f32 v[14:15], v[198:199], s[30:31], v[166:167] op_sel_hi:[1,0,1]
	v_pk_fma_f32 v[16:17], v[200:201], s[30:31], v[168:169] op_sel_hi:[1,0,1]
	v_pk_fma_f32 v[18:19], v[202:203], s[30:31], v[170:171] op_sel_hi:[1,0,1]
	v_pk_fma_f32 v[20:21], v[204:205], s[30:31], v[172:173] op_sel_hi:[1,0,1]
	v_pk_fma_f32 v[22:23], v[206:207], s[30:31], v[174:175] op_sel_hi:[1,0,1]
	v_pk_fma_f32 v[24:25], v[208:209], s[30:31], v[176:177] op_sel_hi:[1,0,1]
	v_pk_fma_f32 v[26:27], v[210:211], s[30:31], v[178:179] op_sel_hi:[1,0,1]
	v_pk_fma_f32 v[28:29], v[212:213], s[30:31], v[180:181] op_sel_hi:[1,0,1]
	v_pk_fma_f32 v[30:31], v[214:215], s[30:31], v[182:183] op_sel_hi:[1,0,1]
	v_pk_fma_f32 v[32:33], v[216:217], s[30:31], v[184:185] op_sel_hi:[1,0,1]
	v_readlane_b32 s86, v253, 8
	v_readlane_b32 s87, v253, 9
	v_readlane_b32 s92, v253, 10
	v_readlane_b32 s93, v253, 11
	s_lshl_b32 s0, s38, 3
	s_add_u32 s44, s62, 0xf000000
	s_addc_u32 s45, s63, 0
	s_add_u32 s44, s44, s0
	s_addc_u32 s45, s45, 0
	v_lshl_add_u64 v[230:231], s[66:67], 0, v[228:229]
	v_lshrrev_b64 v[222:223], 1, v[228:229]
	v_lshl_add_u64 v[222:223], s[60:61], 0, v[222:223]
	s_nop 2
	global_load_dwordx4 v[186:189], v226, s[86:87] offset:0
	global_load_dwordx4 v[190:193], v226, s[86:87] offset:16
	global_load_dwordx4 v[194:197], v226, s[86:87] offset:512
	global_load_dwordx4 v[198:201], v226, s[86:87] offset:528
	global_load_dwordx4 v[202:205], v226, s[92:93] offset:0
	global_load_dwordx4 v[206:209], v226, s[92:93] offset:16
	global_load_dwordx4 v[210:213], v226, s[92:93] offset:512
	global_load_dwordx4 v[214:217], v226, s[92:93] offset:528
	v_pk_add_f32 v[154:155], v[98:99], v[100:101]
	v_pk_add_f32 v[156:157], v[106:107], v[108:109]
	v_pk_add_f32 v[158:159], v[114:115], v[116:117]
	v_pk_add_f32 v[160:161], v[122:123], v[124:125]
	v_pk_add_f32 v[162:163], v[34:35], v[36:37]
	v_pk_add_f32 v[164:165], v[42:43], v[44:45]
	v_pk_add_f32 v[166:167], v[50:51], v[52:53]
	v_pk_add_f32 v[168:169], v[58:59], v[60:61]
	v_pk_add_f32 v[154:155], v[154:155], v[102:103]
	v_pk_add_f32 v[156:157], v[156:157], v[110:111]
	v_pk_add_f32 v[158:159], v[158:159], v[118:119]
	v_pk_add_f32 v[160:161], v[160:161], v[126:127]
	v_pk_add_f32 v[162:163], v[162:163], v[38:39]
	v_pk_add_f32 v[164:165], v[164:165], v[46:47]
	v_pk_add_f32 v[166:167], v[166:167], v[54:55]
	v_pk_add_f32 v[168:169], v[168:169], v[62:63]
	v_pk_add_f32 v[154:155], v[154:155], v[104:105]
	v_pk_add_f32 v[156:157], v[156:157], v[112:113]
	v_pk_add_f32 v[158:159], v[158:159], v[120:121]
	v_pk_add_f32 v[160:161], v[160:161], v[128:129]
	v_pk_add_f32 v[162:163], v[162:163], v[40:41]
	v_pk_add_f32 v[164:165], v[164:165], v[48:49]
	v_pk_add_f32 v[166:167], v[166:167], v[56:57]
	v_pk_add_f32 v[168:169], v[168:169], v[64:65]
	v_pk_add_f32 v[154:155], v[154:155], v[66:67]
	v_pk_add_f32 v[156:157], v[156:157], v[74:75]
	v_pk_add_f32 v[158:159], v[158:159], v[82:83]
	v_pk_add_f32 v[160:161], v[160:161], v[90:91]
	v_pk_add_f32 v[162:163], v[162:163], v[2:3]
	v_pk_add_f32 v[164:165], v[164:165], v[10:11]
	v_pk_add_f32 v[166:167], v[166:167], v[18:19]
	v_pk_add_f32 v[168:169], v[168:169], v[26:27]
	v_pk_add_f32 v[154:155], v[154:155], v[68:69]
	v_pk_add_f32 v[156:157], v[156:157], v[76:77]
	v_pk_add_f32 v[158:159], v[158:159], v[84:85]
	v_pk_add_f32 v[160:161], v[160:161], v[92:93]
	v_pk_add_f32 v[162:163], v[162:163], v[4:5]
	v_pk_add_f32 v[164:165], v[164:165], v[12:13]
	v_pk_add_f32 v[166:167], v[166:167], v[20:21]
	v_pk_add_f32 v[168:169], v[168:169], v[28:29]
	v_pk_add_f32 v[154:155], v[154:155], v[70:71]
	v_pk_add_f32 v[156:157], v[156:157], v[78:79]
	v_pk_add_f32 v[158:159], v[158:159], v[86:87]
	v_pk_add_f32 v[160:161], v[160:161], v[94:95]
	v_pk_add_f32 v[162:163], v[162:163], v[6:7]
	v_pk_add_f32 v[164:165], v[164:165], v[14:15]
	v_pk_add_f32 v[166:167], v[166:167], v[22:23]
	v_pk_add_f32 v[168:169], v[168:169], v[30:31]
	v_pk_add_f32 v[154:155], v[154:155], v[72:73]
	v_pk_add_f32 v[156:157], v[156:157], v[80:81]
	v_pk_add_f32 v[158:159], v[158:159], v[88:89]
	v_pk_add_f32 v[160:161], v[160:161], v[96:97]
	v_pk_add_f32 v[162:163], v[162:163], v[8:9]
	v_pk_add_f32 v[164:165], v[164:165], v[16:17]
	v_pk_add_f32 v[166:167], v[166:167], v[24:25]
	v_pk_add_f32 v[168:169], v[168:169], v[32:33]
	v_add_f32_e32 v132, v154, v155
	v_add_f32_e32 v134, v156, v157
	v_add_f32_e32 v136, v158, v159
	v_add_f32_e32 v138, v160, v161
	v_add_f32_e32 v232, v162, v163
	v_add_f32_e32 v234, v164, v165
	v_add_f32_e32 v236, v166, v167
	v_add_f32_e32 v150, v168, v169
	v_add_f32_dpp v132, v132, v132 quad_perm:[1,0,3,2] row_mask:0xf bank_mask:0xf
	v_add_f32_dpp v134, v134, v134 quad_perm:[1,0,3,2] row_mask:0xf bank_mask:0xf
	v_add_f32_dpp v136, v136, v136 quad_perm:[1,0,3,2] row_mask:0xf bank_mask:0xf
	v_add_f32_dpp v138, v138, v138 quad_perm:[1,0,3,2] row_mask:0xf bank_mask:0xf
	v_add_f32_dpp v232, v232, v232 quad_perm:[1,0,3,2] row_mask:0xf bank_mask:0xf
	v_add_f32_dpp v234, v234, v234 quad_perm:[1,0,3,2] row_mask:0xf bank_mask:0xf
	v_add_f32_dpp v236, v236, v236 quad_perm:[1,0,3,2] row_mask:0xf bank_mask:0xf
	v_add_f32_dpp v150, v150, v150 quad_perm:[1,0,3,2] row_mask:0xf bank_mask:0xf
	v_add_f32_dpp v132, v132, v132 quad_perm:[2,3,0,1] row_mask:0xf bank_mask:0xf
	v_add_f32_dpp v134, v134, v134 quad_perm:[2,3,0,1] row_mask:0xf bank_mask:0xf
	v_add_f32_dpp v136, v136, v136 quad_perm:[2,3,0,1] row_mask:0xf bank_mask:0xf
	v_add_f32_dpp v138, v138, v138 quad_perm:[2,3,0,1] row_mask:0xf bank_mask:0xf
	v_add_f32_dpp v232, v232, v232 quad_perm:[2,3,0,1] row_mask:0xf bank_mask:0xf
	v_add_f32_dpp v234, v234, v234 quad_perm:[2,3,0,1] row_mask:0xf bank_mask:0xf
	v_add_f32_dpp v236, v236, v236 quad_perm:[2,3,0,1] row_mask:0xf bank_mask:0xf
	v_add_f32_dpp v150, v150, v150 quad_perm:[2,3,0,1] row_mask:0xf bank_mask:0xf
	v_add_f32_dpp v132, v132, v132 row_half_mirror row_mask:0xf bank_mask:0xf
	v_add_f32_dpp v134, v134, v134 row_half_mirror row_mask:0xf bank_mask:0xf
	v_add_f32_dpp v136, v136, v136 row_half_mirror row_mask:0xf bank_mask:0xf
	v_add_f32_dpp v138, v138, v138 row_half_mirror row_mask:0xf bank_mask:0xf
	v_add_f32_dpp v232, v232, v232 row_half_mirror row_mask:0xf bank_mask:0xf
	v_add_f32_dpp v234, v234, v234 row_half_mirror row_mask:0xf bank_mask:0xf
	v_add_f32_dpp v236, v236, v236 row_half_mirror row_mask:0xf bank_mask:0xf
	v_add_f32_dpp v150, v150, v150 row_half_mirror row_mask:0xf bank_mask:0xf
	v_add_f32_dpp v132, v132, v132 row_mirror row_mask:0xf bank_mask:0xf
	v_add_f32_dpp v134, v134, v134 row_mirror row_mask:0xf bank_mask:0xf
	v_add_f32_dpp v136, v136, v136 row_mirror row_mask:0xf bank_mask:0xf
	v_add_f32_dpp v138, v138, v138 row_mirror row_mask:0xf bank_mask:0xf
	v_add_f32_dpp v232, v232, v232 row_mirror row_mask:0xf bank_mask:0xf
	v_add_f32_dpp v234, v234, v234 row_mirror row_mask:0xf bank_mask:0xf
	v_add_f32_dpp v236, v236, v236 row_mirror row_mask:0xf bank_mask:0xf
	v_add_f32_dpp v150, v150, v150 row_mirror row_mask:0xf bank_mask:0xf
	v_mul_f32_e32 v132, 0x3b800000, v132
	v_mul_f32_e32 v134, 0x3b800000, v134
	v_mul_f32_e32 v136, 0x3b800000, v136
	v_mul_f32_e32 v138, 0x3b800000, v138
	v_mul_f32_e32 v232, 0x3b800000, v232
	v_mul_f32_e32 v234, 0x3b800000, v234
	v_mul_f32_e32 v236, 0x3b800000, v236
	v_mul_f32_e32 v150, 0x3b800000, v150
	v_pk_add_f32 v[218:219], v[98:99], v[132:133] op_sel_hi:[1,0] neg_lo:[0,1] neg_hi:[0,1]
	v_pk_mul_f32 v[170:171], v[218:219], v[218:219]
	v_pk_add_f32 v[220:221], v[106:107], v[134:135] op_sel_hi:[1,0] neg_lo:[0,1] neg_hi:[0,1]
	v_pk_mul_f32 v[172:173], v[220:221], v[220:221]
	v_pk_add_f32 v[218:219], v[114:115], v[136:137] op_sel_hi:[1,0] neg_lo:[0,1] neg_hi:[0,1]
	v_pk_mul_f32 v[174:175], v[218:219], v[218:219]
	v_pk_add_f32 v[220:221], v[122:123], v[138:139] op_sel_hi:[1,0] neg_lo:[0,1] neg_hi:[0,1]
	v_pk_mul_f32 v[176:177], v[220:221], v[220:221]
	v_pk_add_f32 v[218:219], v[34:35], v[232:233] op_sel_hi:[1,0] neg_lo:[0,1] neg_hi:[0,1]
	v_pk_mul_f32 v[178:179], v[218:219], v[218:219]
	v_pk_add_f32 v[220:221], v[42:43], v[234:235] op_sel_hi:[1,0] neg_lo:[0,1] neg_hi:[0,1]
	v_pk_mul_f32 v[180:181], v[220:221], v[220:221]
	v_pk_add_f32 v[218:219], v[50:51], v[236:237] op_sel_hi:[1,0] neg_lo:[0,1] neg_hi:[0,1]
	v_pk_mul_f32 v[182:183], v[218:219], v[218:219]
	v_pk_add_f32 v[220:221], v[58:59], v[150:151] op_sel_hi:[1,0] neg_lo:[0,1] neg_hi:[0,1]
	v_pk_mul_f32 v[184:185], v[220:221], v[220:221]
	v_pk_add_f32 v[218:219], v[100:101], v[132:133] op_sel_hi:[1,0] neg_lo:[0,1] neg_hi:[0,1]
	v_pk_fma_f32 v[170:171], v[218:219], v[218:219], v[170:171]
	v_pk_add_f32 v[220:221], v[108:109], v[134:135] op_sel_hi:[1,0] neg_lo:[0,1] neg_hi:[0,1]
	v_pk_fma_f32 v[172:173], v[220:221], v[220:221], v[172:173]
	v_pk_add_f32 v[218:219], v[116:117], v[136:137] op_sel_hi:[1,0] neg_lo:[0,1] neg_hi:[0,1]
	v_pk_fma_f32 v[174:175], v[218:219], v[218:219], v[174:175]
	v_pk_add_f32 v[220:221], v[124:125], v[138:139] op_sel_hi:[1,0] neg_lo:[0,1] neg_hi:[0,1]
	v_pk_fma_f32 v[176:177], v[220:221], v[220:221], v[176:177]
	v_pk_add_f32 v[218:219], v[36:37], v[232:233] op_sel_hi:[1,0] neg_lo:[0,1] neg_hi:[0,1]
	v_pk_fma_f32 v[178:179], v[218:219], v[218:219], v[178:179]
	v_pk_add_f32 v[220:221], v[44:45], v[234:235] op_sel_hi:[1,0] neg_lo:[0,1] neg_hi:[0,1]
	v_pk_fma_f32 v[180:181], v[220:221], v[220:221], v[180:181]
	v_pk_add_f32 v[218:219], v[52:53], v[236:237] op_sel_hi:[1,0] neg_lo:[0,1] neg_hi:[0,1]
	v_pk_fma_f32 v[182:183], v[218:219], v[218:219], v[182:183]
	v_pk_add_f32 v[220:221], v[60:61], v[150:151] op_sel_hi:[1,0] neg_lo:[0,1] neg_hi:[0,1]
	v_pk_fma_f32 v[184:185], v[220:221], v[220:221], v[184:185]
	v_pk_add_f32 v[218:219], v[102:103], v[132:133] op_sel_hi:[1,0] neg_lo:[0,1] neg_hi:[0,1]
	v_pk_fma_f32 v[170:171], v[218:219], v[218:219], v[170:171]
	v_pk_add_f32 v[220:221], v[110:111], v[134:135] op_sel_hi:[1,0] neg_lo:[0,1] neg_hi:[0,1]
	v_pk_fma_f32 v[172:173], v[220:221], v[220:221], v[172:173]
	v_pk_add_f32 v[218:219], v[118:119], v[136:137] op_sel_hi:[1,0] neg_lo:[0,1] neg_hi:[0,1]
	v_pk_fma_f32 v[174:175], v[218:219], v[218:219], v[174:175]
	v_pk_add_f32 v[220:221], v[126:127], v[138:139] op_sel_hi:[1,0] neg_lo:[0,1] neg_hi:[0,1]
	v_pk_fma_f32 v[176:177], v[220:221], v[220:221], v[176:177]
	v_pk_add_f32 v[218:219], v[38:39], v[232:233] op_sel_hi:[1,0] neg_lo:[0,1] neg_hi:[0,1]
	v_pk_fma_f32 v[178:179], v[218:219], v[218:219], v[178:179]
	v_pk_add_f32 v[220:221], v[46:47], v[234:235] op_sel_hi:[1,0] neg_lo:[0,1] neg_hi:[0,1]
	v_pk_fma_f32 v[180:181], v[220:221], v[220:221], v[180:181]
	v_pk_add_f32 v[218:219], v[54:55], v[236:237] op_sel_hi:[1,0] neg_lo:[0,1] neg_hi:[0,1]
	v_pk_fma_f32 v[182:183], v[218:219], v[218:219], v[182:183]
	v_pk_add_f32 v[220:221], v[62:63], v[150:151] op_sel_hi:[1,0] neg_lo:[0,1] neg_hi:[0,1]
	v_pk_fma_f32 v[184:185], v[220:221], v[220:221], v[184:185]
	v_pk_add_f32 v[218:219], v[104:105], v[132:133] op_sel_hi:[1,0] neg_lo:[0,1] neg_hi:[0,1]
	v_pk_fma_f32 v[170:171], v[218:219], v[218:219], v[170:171]
	v_pk_add_f32 v[220:221], v[112:113], v[134:135] op_sel_hi:[1,0] neg_lo:[0,1] neg_hi:[0,1]
	v_pk_fma_f32 v[172:173], v[220:221], v[220:221], v[172:173]
	v_pk_add_f32 v[218:219], v[120:121], v[136:137] op_sel_hi:[1,0] neg_lo:[0,1] neg_hi:[0,1]
	v_pk_fma_f32 v[174:175], v[218:219], v[218:219], v[174:175]
	v_pk_add_f32 v[220:221], v[128:129], v[138:139] op_sel_hi:[1,0] neg_lo:[0,1] neg_hi:[0,1]
	v_pk_fma_f32 v[176:177], v[220:221], v[220:221], v[176:177]
	v_pk_add_f32 v[218:219], v[40:41], v[232:233] op_sel_hi:[1,0] neg_lo:[0,1] neg_hi:[0,1]
	v_pk_fma_f32 v[178:179], v[218:219], v[218:219], v[178:179]
	v_pk_add_f32 v[220:221], v[48:49], v[234:235] op_sel_hi:[1,0] neg_lo:[0,1] neg_hi:[0,1]
	v_pk_fma_f32 v[180:181], v[220:221], v[220:221], v[180:181]
	v_pk_add_f32 v[218:219], v[56:57], v[236:237] op_sel_hi:[1,0] neg_lo:[0,1] neg_hi:[0,1]
	v_pk_fma_f32 v[182:183], v[218:219], v[218:219], v[182:183]
	v_pk_add_f32 v[220:221], v[64:65], v[150:151] op_sel_hi:[1,0] neg_lo:[0,1] neg_hi:[0,1]
	v_pk_fma_f32 v[184:185], v[220:221], v[220:221], v[184:185]
	v_pk_add_f32 v[218:219], v[66:67], v[132:133] op_sel_hi:[1,0] neg_lo:[0,1] neg_hi:[0,1]
	v_pk_fma_f32 v[170:171], v[218:219], v[218:219], v[170:171]
	v_pk_add_f32 v[220:221], v[74:75], v[134:135] op_sel_hi:[1,0] neg_lo:[0,1] neg_hi:[0,1]
	v_pk_fma_f32 v[172:173], v[220:221], v[220:221], v[172:173]
	v_pk_add_f32 v[218:219], v[82:83], v[136:137] op_sel_hi:[1,0] neg_lo:[0,1] neg_hi:[0,1]
	v_pk_fma_f32 v[174:175], v[218:219], v[218:219], v[174:175]
	v_pk_add_f32 v[220:221], v[90:91], v[138:139] op_sel_hi:[1,0] neg_lo:[0,1] neg_hi:[0,1]
	v_pk_fma_f32 v[176:177], v[220:221], v[220:221], v[176:177]
	v_pk_add_f32 v[218:219], v[2:3], v[232:233] op_sel_hi:[1,0] neg_lo:[0,1] neg_hi:[0,1]
	v_pk_fma_f32 v[178:179], v[218:219], v[218:219], v[178:179]
	v_pk_add_f32 v[220:221], v[10:11], v[234:235] op_sel_hi:[1,0] neg_lo:[0,1] neg_hi:[0,1]
	v_pk_fma_f32 v[180:181], v[220:221], v[220:221], v[180:181]
	v_pk_add_f32 v[218:219], v[18:19], v[236:237] op_sel_hi:[1,0] neg_lo:[0,1] neg_hi:[0,1]
	v_pk_fma_f32 v[182:183], v[218:219], v[218:219], v[182:183]
	v_pk_add_f32 v[220:221], v[26:27], v[150:151] op_sel_hi:[1,0] neg_lo:[0,1] neg_hi:[0,1]
	v_pk_fma_f32 v[184:185], v[220:221], v[220:221], v[184:185]
	v_pk_add_f32 v[218:219], v[68:69], v[132:133] op_sel_hi:[1,0] neg_lo:[0,1] neg_hi:[0,1]
	v_pk_fma_f32 v[170:171], v[218:219], v[218:219], v[170:171]
	v_pk_add_f32 v[220:221], v[76:77], v[134:135] op_sel_hi:[1,0] neg_lo:[0,1] neg_hi:[0,1]
	v_pk_fma_f32 v[172:173], v[220:221], v[220:221], v[172:173]
	v_pk_add_f32 v[218:219], v[84:85], v[136:137] op_sel_hi:[1,0] neg_lo:[0,1] neg_hi:[0,1]
	v_pk_fma_f32 v[174:175], v[218:219], v[218:219], v[174:175]
	v_pk_add_f32 v[220:221], v[92:93], v[138:139] op_sel_hi:[1,0] neg_lo:[0,1] neg_hi:[0,1]
	v_pk_fma_f32 v[176:177], v[220:221], v[220:221], v[176:177]
	v_pk_add_f32 v[218:219], v[4:5], v[232:233] op_sel_hi:[1,0] neg_lo:[0,1] neg_hi:[0,1]
	v_pk_fma_f32 v[178:179], v[218:219], v[218:219], v[178:179]
	v_pk_add_f32 v[220:221], v[12:13], v[234:235] op_sel_hi:[1,0] neg_lo:[0,1] neg_hi:[0,1]
	v_pk_fma_f32 v[180:181], v[220:221], v[220:221], v[180:181]
	v_pk_add_f32 v[218:219], v[20:21], v[236:237] op_sel_hi:[1,0] neg_lo:[0,1] neg_hi:[0,1]
	v_pk_fma_f32 v[182:183], v[218:219], v[218:219], v[182:183]
	v_pk_add_f32 v[220:221], v[28:29], v[150:151] op_sel_hi:[1,0] neg_lo:[0,1] neg_hi:[0,1]
	v_pk_fma_f32 v[184:185], v[220:221], v[220:221], v[184:185]
	v_pk_add_f32 v[218:219], v[70:71], v[132:133] op_sel_hi:[1,0] neg_lo:[0,1] neg_hi:[0,1]
	v_pk_fma_f32 v[170:171], v[218:219], v[218:219], v[170:171]
	v_pk_add_f32 v[220:221], v[78:79], v[134:135] op_sel_hi:[1,0] neg_lo:[0,1] neg_hi:[0,1]
	v_pk_fma_f32 v[172:173], v[220:221], v[220:221], v[172:173]
	v_pk_add_f32 v[218:219], v[86:87], v[136:137] op_sel_hi:[1,0] neg_lo:[0,1] neg_hi:[0,1]
	v_pk_fma_f32 v[174:175], v[218:219], v[218:219], v[174:175]
	v_pk_add_f32 v[220:221], v[94:95], v[138:139] op_sel_hi:[1,0] neg_lo:[0,1] neg_hi:[0,1]
	v_pk_fma_f32 v[176:177], v[220:221], v[220:221], v[176:177]
	v_pk_add_f32 v[218:219], v[6:7], v[232:233] op_sel_hi:[1,0] neg_lo:[0,1] neg_hi:[0,1]
	v_pk_fma_f32 v[178:179], v[218:219], v[218:219], v[178:179]
	v_pk_add_f32 v[220:221], v[14:15], v[234:235] op_sel_hi:[1,0] neg_lo:[0,1] neg_hi:[0,1]
	v_pk_fma_f32 v[180:181], v[220:221], v[220:221], v[180:181]
	v_pk_add_f32 v[218:219], v[22:23], v[236:237] op_sel_hi:[1,0] neg_lo:[0,1] neg_hi:[0,1]
	v_pk_fma_f32 v[182:183], v[218:219], v[218:219], v[182:183]
	v_pk_add_f32 v[220:221], v[30:31], v[150:151] op_sel_hi:[1,0] neg_lo:[0,1] neg_hi:[0,1]
	v_pk_fma_f32 v[184:185], v[220:221], v[220:221], v[184:185]
	v_pk_add_f32 v[218:219], v[72:73], v[132:133] op_sel_hi:[1,0] neg_lo:[0,1] neg_hi:[0,1]
	v_pk_fma_f32 v[170:171], v[218:219], v[218:219], v[170:171]
	v_pk_add_f32 v[220:221], v[80:81], v[134:135] op_sel_hi:[1,0] neg_lo:[0,1] neg_hi:[0,1]
	v_pk_fma_f32 v[172:173], v[220:221], v[220:221], v[172:173]
	v_pk_add_f32 v[218:219], v[88:89], v[136:137] op_sel_hi:[1,0] neg_lo:[0,1] neg_hi:[0,1]
	v_pk_fma_f32 v[174:175], v[218:219], v[218:219], v[174:175]
	v_pk_add_f32 v[220:221], v[96:97], v[138:139] op_sel_hi:[1,0] neg_lo:[0,1] neg_hi:[0,1]
	v_pk_fma_f32 v[176:177], v[220:221], v[220:221], v[176:177]
	v_pk_add_f32 v[218:219], v[8:9], v[232:233] op_sel_hi:[1,0] neg_lo:[0,1] neg_hi:[0,1]
	v_pk_fma_f32 v[178:179], v[218:219], v[218:219], v[178:179]
	v_pk_add_f32 v[220:221], v[16:17], v[234:235] op_sel_hi:[1,0] neg_lo:[0,1] neg_hi:[0,1]
	v_pk_fma_f32 v[180:181], v[220:221], v[220:221], v[180:181]
	v_pk_add_f32 v[218:219], v[24:25], v[236:237] op_sel_hi:[1,0] neg_lo:[0,1] neg_hi:[0,1]
	v_pk_fma_f32 v[182:183], v[218:219], v[218:219], v[182:183]
	v_pk_add_f32 v[220:221], v[32:33], v[150:151] op_sel_hi:[1,0] neg_lo:[0,1] neg_hi:[0,1]
	v_pk_fma_f32 v[184:185], v[220:221], v[220:221], v[184:185]
	v_add_f32_e32 v133, v170, v171
	v_add_f32_e32 v135, v172, v173
	v_add_f32_e32 v137, v174, v175
	v_add_f32_e32 v139, v176, v177
	v_add_f32_e32 v233, v178, v179
	v_add_f32_e32 v235, v180, v181
	v_add_f32_e32 v237, v182, v183
	v_add_f32_e32 v151, v184, v185
	v_add_f32_dpp v133, v133, v133 quad_perm:[1,0,3,2] row_mask:0xf bank_mask:0xf
	v_add_f32_dpp v135, v135, v135 quad_perm:[1,0,3,2] row_mask:0xf bank_mask:0xf
	v_add_f32_dpp v137, v137, v137 quad_perm:[1,0,3,2] row_mask:0xf bank_mask:0xf
	v_add_f32_dpp v139, v139, v139 quad_perm:[1,0,3,2] row_mask:0xf bank_mask:0xf
	v_add_f32_dpp v233, v233, v233 quad_perm:[1,0,3,2] row_mask:0xf bank_mask:0xf
	v_add_f32_dpp v235, v235, v235 quad_perm:[1,0,3,2] row_mask:0xf bank_mask:0xf
	v_add_f32_dpp v237, v237, v237 quad_perm:[1,0,3,2] row_mask:0xf bank_mask:0xf
	v_add_f32_dpp v151, v151, v151 quad_perm:[1,0,3,2] row_mask:0xf bank_mask:0xf
	v_add_f32_dpp v133, v133, v133 quad_perm:[2,3,0,1] row_mask:0xf bank_mask:0xf
	v_add_f32_dpp v135, v135, v135 quad_perm:[2,3,0,1] row_mask:0xf bank_mask:0xf
	v_add_f32_dpp v137, v137, v137 quad_perm:[2,3,0,1] row_mask:0xf bank_mask:0xf
	v_add_f32_dpp v139, v139, v139 quad_perm:[2,3,0,1] row_mask:0xf bank_mask:0xf
	v_add_f32_dpp v233, v233, v233 quad_perm:[2,3,0,1] row_mask:0xf bank_mask:0xf
	v_add_f32_dpp v235, v235, v235 quad_perm:[2,3,0,1] row_mask:0xf bank_mask:0xf
	v_add_f32_dpp v237, v237, v237 quad_perm:[2,3,0,1] row_mask:0xf bank_mask:0xf
	v_add_f32_dpp v151, v151, v151 quad_perm:[2,3,0,1] row_mask:0xf bank_mask:0xf
	v_add_f32_dpp v133, v133, v133 row_half_mirror row_mask:0xf bank_mask:0xf
	v_add_f32_dpp v135, v135, v135 row_half_mirror row_mask:0xf bank_mask:0xf
	v_add_f32_dpp v137, v137, v137 row_half_mirror row_mask:0xf bank_mask:0xf
	v_add_f32_dpp v139, v139, v139 row_half_mirror row_mask:0xf bank_mask:0xf
	v_add_f32_dpp v233, v233, v233 row_half_mirror row_mask:0xf bank_mask:0xf
	v_add_f32_dpp v235, v235, v235 row_half_mirror row_mask:0xf bank_mask:0xf
	v_add_f32_dpp v237, v237, v237 row_half_mirror row_mask:0xf bank_mask:0xf
	v_add_f32_dpp v151, v151, v151 row_half_mirror row_mask:0xf bank_mask:0xf
	v_add_f32_dpp v133, v133, v133 row_mirror row_mask:0xf bank_mask:0xf
	v_add_f32_dpp v135, v135, v135 row_mirror row_mask:0xf bank_mask:0xf
	v_add_f32_dpp v137, v137, v137 row_mirror row_mask:0xf bank_mask:0xf
	v_add_f32_dpp v139, v139, v139 row_mirror row_mask:0xf bank_mask:0xf
	v_add_f32_dpp v233, v233, v233 row_mirror row_mask:0xf bank_mask:0xf
	v_add_f32_dpp v235, v235, v235 row_mirror row_mask:0xf bank_mask:0xf
	v_add_f32_dpp v237, v237, v237 row_mirror row_mask:0xf bank_mask:0xf
	v_add_f32_dpp v151, v151, v151 row_mirror row_mask:0xf bank_mask:0xf
	s_lshr_b32 s0, s38, 8
	s_lshl_b32 s0, s0, 13
	s_add_u32 s74, s62, 0xf100000
	s_addc_u32 s75, s63, 0
	s_add_u32 s74, s74, s0
	s_addc_u32 s75, s75, 0
	s_lshr_b32 s0, s36, 8
	s_lshl_b32 s0, s0, 11
	v_add_u32_e32 v224, s0, v227
	s_mov_b32 exec_lo, 0x10001
	s_mov_b32 exec_hi, 0x10001
	global_store_dwordx2 v224, v[132:133], s[74:75] offset:0 sc1
	global_store_dwordx2 v224, v[134:135], s[74:75] offset:256 sc1
	global_store_dwordx2 v224, v[136:137], s[74:75] offset:512 sc1
	global_store_dwordx2 v224, v[138:139], s[74:75] offset:768 sc1
	global_store_dwordx2 v224, v[232:233], s[74:75] offset:1024 sc1
	global_store_dwordx2 v224, v[234:235], s[74:75] offset:1280 sc1
	global_store_dwordx2 v224, v[236:237], s[74:75] offset:1536 sc1
	global_store_dwordx2 v224, v[150:151], s[74:75] offset:1792 sc1
	s_mov_b64 exec, -1
	s_waitcnt vmcnt(0)
	s_barrier
	v_readfirstlane_b32 s99, v0
	s_nop 3
	s_lshr_b32 s99, s99, 6
	s_cmp_lg_u32 s99, 0
	s_cbranch_scc0 .Lp6_signal
	s_mov_b32 s70, 0x0
	s_mov_b32 s71, 0
	v_lshl_add_u64 v[154:155], v[230:231], 0, s[70:71]
	global_store_dwordx4 v[154:155], v[98:101], off
	global_store_dwordx4 v[154:155], v[102:105], off offset:16
	s_mov_b32 s70, 0x20000
	s_mov_b32 s71, 0
	v_lshl_add_u64 v[156:157], v[230:231], 0, s[70:71]
	global_store_dwordx4 v[156:157], v[106:109], off
	global_store_dwordx4 v[156:157], v[110:113], off offset:16
	s_mov_b32 s70, 0x40000
	s_mov_b32 s71, 0
	v_lshl_add_u64 v[154:155], v[230:231], 0, s[70:71]
	global_store_dwordx4 v[154:155], v[114:117], off
	global_store_dwordx4 v[154:155], v[118:121], off offset:16
	s_mov_b32 s70, 0x60000
	s_mov_b32 s71, 0
	v_lshl_add_u64 v[156:157], v[230:231], 0, s[70:71]
	global_store_dwordx4 v[156:157], v[122:125], off
	global_store_dwordx4 v[156:157], v[126:129], off offset:16
	s_mov_b32 s70, 0x200
	s_mov_b32 s71, 0
	v_lshl_add_u64 v[154:155], v[230:231], 0, s[70:71]
	global_store_dwordx4 v[154:155], v[66:69], off
	global_store_dwordx4 v[154:155], v[70:73], off offset:16
	s_mov_b32 s70, 0x20200
	s_mov_b32 s71, 0
	v_lshl_add_u64 v[156:157], v[230:231], 0, s[70:71]
	global_store_dwordx4 v[156:157], v[74:77], off
	global_store_dwordx4 v[156:157], v[78:81], off offset:16
	s_mov_b32 s70, 0x40200
	s_mov_b32 s71, 0
	v_lshl_add_u64 v[154:155], v[230:231], 0, s[70:71]
	global_store_dwordx4 v[154:155], v[82:85], off
	global_store_dwordx4 v[154:155], v[86:89], off offset:16
	s_mov_b32 s70, 0x60200
	s_mov_b32 s71, 0
	v_lshl_add_u64 v[156:157], v[230:231], 0, s[70:71]
	global_store_dwordx4 v[156:157], v[90:93], off
	global_store_dwordx4 v[156:157], v[94:97], off offset:16
	s_mov_b32 s70, 0x80000
	s_mov_b32 s71, 0
	v_lshl_add_u64 v[154:155], v[230:231], 0, s[70:71]
	global_store_dwordx4 v[154:155], v[34:37], off
	global_store_dwordx4 v[154:155], v[38:41], off offset:16
	s_mov_b32 s70, 0xa0000
	s_mov_b32 s71, 0
	v_lshl_add_u64 v[156:157], v[230:231], 0, s[70:71]
	global_store_dwordx4 v[156:157], v[42:45], off
	global_store_dwordx4 v[156:157], v[46:49], off offset:16
	s_mov_b32 s70, 0xc0000
	s_mov_b32 s71, 0
	v_lshl_add_u64 v[154:155], v[230:231], 0, s[70:71]
	global_store_dwordx4 v[154:155], v[50:53], off
	global_store_dwordx4 v[154:155], v[54:57], off offset:16
	s_mov_b32 s70, 0xe0000
	s_mov_b32 s71, 0
	v_lshl_add_u64 v[156:157], v[230:231], 0, s[70:71]
	global_store_dwordx4 v[156:157], v[58:61], off
	global_store_dwordx4 v[156:157], v[62:65], off offset:16
	s_mov_b32 s70, 0x80200
	s_mov_b32 s71, 0
	v_lshl_add_u64 v[154:155], v[230:231], 0, s[70:71]
	global_store_dwordx4 v[154:155], v[2:5], off
	global_store_dwordx4 v[154:155], v[6:9], off offset:16
	s_mov_b32 s70, 0xa0200
	s_mov_b32 s71, 0
	v_lshl_add_u64 v[156:157], v[230:231], 0, s[70:71]
	global_store_dwordx4 v[156:157], v[10:13], off
	global_store_dwordx4 v[156:157], v[14:17], off offset:16
	s_mov_b32 s70, 0xc0200
	s_mov_b32 s71, 0
	v_lshl_add_u64 v[154:155], v[230:231], 0, s[70:71]
	global_store_dwordx4 v[154:155], v[18:21], off
	global_store_dwordx4 v[154:155], v[22:25], off offset:16
	s_mov_b32 s70, 0xe0200
	s_mov_b32 s71, 0
	v_lshl_add_u64 v[156:157], v[230:231], 0, s[70:71]
	global_store_dwordx4 v[156:157], v[26:29], off
	global_store_dwordx4 v[156:157], v[30:33], off offset:16
	s_branch .Lp6_wait_done
.Lp6_signal:
	s_lshr_b32 s37, s38, 8
	s_lshl_b32 s37, s37, 2
	s_add_u32 s80, s62, 0xf71a100
	s_addc_u32 s81, s63, 0
	s_add_u32 s80, s80, s37
	s_addc_u32 s81, s81, 0
	v_mov_b32_e32 v238, 0
	v_mov_b32_e32 v239, 1
	s_mov_b64 exec, 1
	global_atomic_add v238, v239, s[80:81]
	s_mov_b32 s37, 0
.Lp6_poll:
	global_load_dword v240, v238, s[80:81] sc1
	s_waitcnt vmcnt(0)
	v_readfirstlane_b32 s99, v240
	s_nop 3
	s_cmp_ge_u32 s99, 4
	s_cbranch_scc1 .Lp6_polled
	s_sleep 1
	s_add_i32 s37, s37, 1
	s_cmp_lt_u32 s37, 0x4000
	s_cbranch_scc1 .Lp6_poll

.Lp6_wait_done:
	s_barrier
	v_and_b32_e32 v246, 7, v0
	v_lshrrev_b32_e32 v247, 2, v246
	v_and_b32_e32 v246, 3, v246
	v_lshlrev_b32_e32 v247, 10, v247
	v_lshl_add_u32 v246, v246, 8, v247
	v_add_u32_e32 v246, v246, v227
	v_add_u32_e32 v247, 0x1000, v246
	global_load_dwordx2 v[238:239], v246, s[74:75] sc1
	global_load_dwordx2 v[240:241], v246, s[74:75] offset:2048 sc1
	global_load_dwordx2 v[242:243], v247, s[74:75] sc1
	global_load_dwordx2 v[244:245], v247, s[74:75] offset:2048 sc1
	v_readfirstlane_b32 s99, v0
	s_nop 3
	s_lshr_b32 s99, s99, 6
	s_cmp_lg_u32 s99, 0
	s_cbranch_scc1 .Lp6_w0done
	s_mov_b32 s70, 0x0
	s_mov_b32 s71, 0
	v_lshl_add_u64 v[154:155], v[230:231], 0, s[70:71]
	global_store_dwordx4 v[154:155], v[98:101], off
	global_store_dwordx4 v[154:155], v[102:105], off offset:16
	s_mov_b32 s70, 0x20000
	s_mov_b32 s71, 0
	v_lshl_add_u64 v[156:157], v[230:231], 0, s[70:71]
	global_store_dwordx4 v[156:157], v[106:109], off
	global_store_dwordx4 v[156:157], v[110:113], off offset:16
	s_mov_b32 s70, 0x40000
	s_mov_b32 s71, 0
	v_lshl_add_u64 v[154:155], v[230:231], 0, s[70:71]
	global_store_dwordx4 v[154:155], v[114:117], off
	global_store_dwordx4 v[154:155], v[118:121], off offset:16
	s_mov_b32 s70, 0x60000
	s_mov_b32 s71, 0
	v_lshl_add_u64 v[156:157], v[230:231], 0, s[70:71]
	global_store_dwordx4 v[156:157], v[122:125], off
	global_store_dwordx4 v[156:157], v[126:129], off offset:16
	s_mov_b32 s70, 0x200
	s_mov_b32 s71, 0
	v_lshl_add_u64 v[154:155], v[230:231], 0, s[70:71]
	global_store_dwordx4 v[154:155], v[66:69], off
	global_store_dwordx4 v[154:155], v[70:73], off offset:16
	s_mov_b32 s70, 0x20200
	s_mov_b32 s71, 0
	v_lshl_add_u64 v[156:157], v[230:231], 0, s[70:71]
	global_store_dwordx4 v[156:157], v[74:77], off
	global_store_dwordx4 v[156:157], v[78:81], off offset:16
	s_mov_b32 s70, 0x40200
	s_mov_b32 s71, 0
	v_lshl_add_u64 v[154:155], v[230:231], 0, s[70:71]
	global_store_dwordx4 v[154:155], v[82:85], off
	global_store_dwordx4 v[154:155], v[86:89], off offset:16
	s_mov_b32 s70, 0x60200
	s_mov_b32 s71, 0
	v_lshl_add_u64 v[156:157], v[230:231], 0, s[70:71]
	global_store_dwordx4 v[156:157], v[90:93], off
	global_store_dwordx4 v[156:157], v[94:97], off offset:16
	s_mov_b32 s70, 0x80000
	s_mov_b32 s71, 0
	v_lshl_add_u64 v[154:155], v[230:231], 0, s[70:71]
	global_store_dwordx4 v[154:155], v[34:37], off
	global_store_dwordx4 v[154:155], v[38:41], off offset:16
	s_mov_b32 s70, 0xa0000
	s_mov_b32 s71, 0
	v_lshl_add_u64 v[156:157], v[230:231], 0, s[70:71]
	global_store_dwordx4 v[156:157], v[42:45], off
	global_store_dwordx4 v[156:157], v[46:49], off offset:16
	s_mov_b32 s70, 0xc0000
	s_mov_b32 s71, 0
	v_lshl_add_u64 v[154:155], v[230:231], 0, s[70:71]
	global_store_dwordx4 v[154:155], v[50:53], off
	global_store_dwordx4 v[154:155], v[54:57], off offset:16
	s_mov_b32 s70, 0xe0000
	s_mov_b32 s71, 0
	v_lshl_add_u64 v[156:157], v[230:231], 0, s[70:71]
	global_store_dwordx4 v[156:157], v[58:61], off
	global_store_dwordx4 v[156:157], v[62:65], off offset:16
	s_mov_b32 s70, 0x80200
	s_mov_b32 s71, 0
	v_lshl_add_u64 v[154:155], v[230:231], 0, s[70:71]
	global_store_dwordx4 v[154:155], v[2:5], off
	global_store_dwordx4 v[154:155], v[6:9], off offset:16
	s_mov_b32 s70, 0xa0200
	s_mov_b32 s71, 0
	v_lshl_add_u64 v[156:157], v[230:231], 0, s[70:71]
	global_store_dwordx4 v[156:157], v[10:13], off
	global_store_dwordx4 v[156:157], v[14:17], off offset:16
	s_mov_b32 s70, 0xc0200
	s_mov_b32 s71, 0
	v_lshl_add_u64 v[154:155], v[230:231], 0, s[70:71]
	global_store_dwordx4 v[154:155], v[18:21], off
	global_store_dwordx4 v[154:155], v[22:25], off offset:16
	s_mov_b32 s70, 0xe0200
	s_mov_b32 s71, 0
	v_lshl_add_u64 v[156:157], v[230:231], 0, s[70:71]
	global_store_dwordx4 v[156:157], v[26:29], off
	global_store_dwordx4 v[156:157], v[30:33], off offset:16
.Lp6_w0done:
	v_mov_b32_e32 v248, 0x3727c5ac
	v_and_b32_e32 v249, 48, v0
	v_lshlrev_b32_e32 v249, 2, v249
	s_waitcnt vmcnt(0)
	v_add_f32_e32 v250, v238, v240
	v_add_f32_e32 v246, v242, v244
	v_add_f32_e32 v250, v250, v246
	v_mul_f32_e32 v250, 0x3e800000, v250
	v_sub_f32_e32 v238, v238, v250
	v_sub_f32_e32 v240, v240, v250
	v_sub_f32_e32 v242, v242, v250
	v_sub_f32_e32 v244, v244, v250
	v_mul_f32_e32 v246, v238, v238
	v_fmac_f32_e32 v246, v240, v240
	v_fmac_f32_e32 v246, v242, v242
	v_fmac_f32_e32 v246, v244, v244
	v_add_f32_e32 v239, v239, v241
	v_add_f32_e32 v243, v243, v245
	v_add_f32_e32 v239, v239, v243
	v_fmamk_f32 v246, v246, 0x43800000, v239
	v_fmamk_f32 v246, v246, 0x3a800000, v248
	v_rsq_f32_e32 v251, v246
	s_nop 0
	v_add_u32_e32 v240, 0, v249
	ds_bpermute_b32 v132, v240, v250
	ds_bpermute_b32 v133, v240, v251
	v_add_u32_e32 v241, 4, v249
	ds_bpermute_b32 v134, v241, v250
	ds_bpermute_b32 v135, v241, v251
	v_add_u32_e32 v240, 8, v249
	ds_bpermute_b32 v136, v240, v250
	ds_bpermute_b32 v137, v240, v251
	v_add_u32_e32 v241, 12, v249
	ds_bpermute_b32 v138, v241, v250
	ds_bpermute_b32 v139, v241, v251
	v_add_u32_e32 v240, 16, v249
	ds_bpermute_b32 v232, v240, v250
	ds_bpermute_b32 v233, v240, v251
	v_add_u32_e32 v241, 20, v249
	ds_bpermute_b32 v234, v241, v250
	ds_bpermute_b32 v235, v241, v251
	v_add_u32_e32 v240, 24, v249
	ds_bpermute_b32 v236, v240, v250
	ds_bpermute_b32 v237, v240, v251
	v_add_u32_e32 v241, 28, v249
	ds_bpermute_b32 v150, v241, v250
	ds_bpermute_b32 v151, v241, v251
	s_waitcnt lgkmcnt(0)
	s_lshr_b32 s0, s36, 8
	s_cmp_lg_u32 s0, 0
	s_cbranch_scc1 .Lp6_nostats
	s_mov_b32 exec_lo, 0x10001
	s_mov_b32 exec_hi, 0x10001
	global_store_dwordx2 v227, v[132:133], s[44:45] offset:0
	global_store_dwordx2 v227, v[134:135], s[44:45] offset:256
	global_store_dwordx2 v227, v[136:137], s[44:45] offset:512
	global_store_dwordx2 v227, v[138:139], s[44:45] offset:768
	global_store_dwordx2 v227, v[232:233], s[44:45] offset:1024
	global_store_dwordx2 v227, v[234:235], s[44:45] offset:1280
	global_store_dwordx2 v227, v[236:237], s[44:45] offset:1536
	global_store_dwordx2 v227, v[150:151], s[44:45] offset:1792
	s_mov_b64 exec, -1
.Lp6_nostats:
	s_mov_b32 s70, 0x0
	s_mov_b32 s71, 0
	v_lshl_add_u64 v[154:155], v[222:223], 0, s[70:71]
	v_pk_add_f32 v[98:99], v[98:99], v[132:133] op_sel_hi:[1,0] neg_lo:[0,1] neg_hi:[0,1]
	v_pk_mul_f32 v[98:99], v[98:99], v[132:133] op_sel:[0,1]
	v_pk_fma_f32 v[98:99], v[186:187], v[98:99], v[202:203]
	v_pk_add_f32 v[100:101], v[100:101], v[132:133] op_sel_hi:[1,0] neg_lo:[0,1] neg_hi:[0,1]
	v_pk_mul_f32 v[100:101], v[100:101], v[132:133] op_sel:[0,1]
	v_pk_fma_f32 v[100:101], v[188:189], v[100:101], v[204:205]
	v_pk_add_f32 v[102:103], v[102:103], v[132:133] op_sel_hi:[1,0] neg_lo:[0,1] neg_hi:[0,1]
	v_pk_mul_f32 v[102:103], v[102:103], v[132:133] op_sel:[0,1]
	v_pk_fma_f32 v[102:103], v[190:191], v[102:103], v[206:207]
	v_pk_add_f32 v[104:105], v[104:105], v[132:133] op_sel_hi:[1,0] neg_lo:[0,1] neg_hi:[0,1]
	v_pk_mul_f32 v[104:105], v[104:105], v[132:133] op_sel:[0,1]
	v_pk_fma_f32 v[104:105], v[192:193], v[104:105], v[208:209]
	v_cvt_pk_bf16_f32 v98, v98, v99
	v_cvt_pk_bf16_f32 v99, v100, v101
	v_cvt_pk_bf16_f32 v100, v102, v103
	v_cvt_pk_bf16_f32 v101, v104, v105
	global_store_dwordx4 v[154:155], v[98:101], off
	s_mov_b32 s70, 0x10000
	s_mov_b32 s71, 0
	v_lshl_add_u64 v[156:157], v[222:223], 0, s[70:71]
	v_pk_add_f32 v[106:107], v[106:107], v[134:135] op_sel_hi:[1,0] neg_lo:[0,1] neg_hi:[0,1]
	v_pk_mul_f32 v[106:107], v[106:107], v[134:135] op_sel:[0,1]
	v_pk_fma_f32 v[106:107], v[186:187], v[106:107], v[202:203]
	v_pk_add_f32 v[108:109], v[108:109], v[134:135] op_sel_hi:[1,0] neg_lo:[0,1] neg_hi:[0,1]
	v_pk_mul_f32 v[108:109], v[108:109], v[134:135] op_sel:[0,1]
	v_pk_fma_f32 v[108:109], v[188:189], v[108:109], v[204:205]
	v_pk_add_f32 v[110:111], v[110:111], v[134:135] op_sel_hi:[1,0] neg_lo:[0,1] neg_hi:[0,1]
	v_pk_mul_f32 v[110:111], v[110:111], v[134:135] op_sel:[0,1]
	v_pk_fma_f32 v[110:111], v[190:191], v[110:111], v[206:207]
	v_pk_add_f32 v[112:113], v[112:113], v[134:135] op_sel_hi:[1,0] neg_lo:[0,1] neg_hi:[0,1]
	v_pk_mul_f32 v[112:113], v[112:113], v[134:135] op_sel:[0,1]
	v_pk_fma_f32 v[112:113], v[192:193], v[112:113], v[208:209]
	v_cvt_pk_bf16_f32 v106, v106, v107
	v_cvt_pk_bf16_f32 v107, v108, v109
	v_cvt_pk_bf16_f32 v108, v110, v111
	v_cvt_pk_bf16_f32 v109, v112, v113
	global_store_dwordx4 v[156:157], v[106:109], off
	s_mov_b32 s70, 0x20000
	s_mov_b32 s71, 0
	v_lshl_add_u64 v[154:155], v[222:223], 0, s[70:71]
	v_pk_add_f32 v[114:115], v[114:115], v[136:137] op_sel_hi:[1,0] neg_lo:[0,1] neg_hi:[0,1]
	v_pk_mul_f32 v[114:115], v[114:115], v[136:137] op_sel:[0,1]
	v_pk_fma_f32 v[114:115], v[186:187], v[114:115], v[202:203]
	v_pk_add_f32 v[116:117], v[116:117], v[136:137] op_sel_hi:[1,0] neg_lo:[0,1] neg_hi:[0,1]
	v_pk_mul_f32 v[116:117], v[116:117], v[136:137] op_sel:[0,1]
	v_pk_fma_f32 v[116:117], v[188:189], v[116:117], v[204:205]
	v_pk_add_f32 v[118:119], v[118:119], v[136:137] op_sel_hi:[1,0] neg_lo:[0,1] neg_hi:[0,1]
	v_pk_mul_f32 v[118:119], v[118:119], v[136:137] op_sel:[0,1]
	v_pk_fma_f32 v[118:119], v[190:191], v[118:119], v[206:207]
	v_pk_add_f32 v[120:121], v[120:121], v[136:137] op_sel_hi:[1,0] neg_lo:[0,1] neg_hi:[0,1]
	v_pk_mul_f32 v[120:121], v[120:121], v[136:137] op_sel:[0,1]
	v_pk_fma_f32 v[120:121], v[192:193], v[120:121], v[208:209]
	v_cvt_pk_bf16_f32 v114, v114, v115
	v_cvt_pk_bf16_f32 v115, v116, v117
	v_cvt_pk_bf16_f32 v116, v118, v119
	v_cvt_pk_bf16_f32 v117, v120, v121
	global_store_dwordx4 v[154:155], v[114:117], off
	s_mov_b32 s70, 0x30000
	s_mov_b32 s71, 0
	v_lshl_add_u64 v[156:157], v[222:223], 0, s[70:71]
	v_pk_add_f32 v[122:123], v[122:123], v[138:139] op_sel_hi:[1,0] neg_lo:[0,1] neg_hi:[0,1]
	v_pk_mul_f32 v[122:123], v[122:123], v[138:139] op_sel:[0,1]
	v_pk_fma_f32 v[122:123], v[186:187], v[122:123], v[202:203]
	v_pk_add_f32 v[124:125], v[124:125], v[138:139] op_sel_hi:[1,0] neg_lo:[0,1] neg_hi:[0,1]
	v_pk_mul_f32 v[124:125], v[124:125], v[138:139] op_sel:[0,1]
	v_pk_fma_f32 v[124:125], v[188:189], v[124:125], v[204:205]
	v_pk_add_f32 v[126:127], v[126:127], v[138:139] op_sel_hi:[1,0] neg_lo:[0,1] neg_hi:[0,1]
	v_pk_mul_f32 v[126:127], v[126:127], v[138:139] op_sel:[0,1]
	v_pk_fma_f32 v[126:127], v[190:191], v[126:127], v[206:207]
	v_pk_add_f32 v[128:129], v[128:129], v[138:139] op_sel_hi:[1,0] neg_lo:[0,1] neg_hi:[0,1]
	v_pk_mul_f32 v[128:129], v[128:129], v[138:139] op_sel:[0,1]
	v_pk_fma_f32 v[128:129], v[192:193], v[128:129], v[208:209]
	v_cvt_pk_bf16_f32 v122, v122, v123
	v_cvt_pk_bf16_f32 v123, v124, v125
	v_cvt_pk_bf16_f32 v124, v126, v127
	v_cvt_pk_bf16_f32 v125, v128, v129
	global_store_dwordx4 v[156:157], v[122:125], off
	s_mov_b32 s70, 0x100
	s_mov_b32 s71, 0
	v_lshl_add_u64 v[154:155], v[222:223], 0, s[70:71]
	v_pk_add_f32 v[66:67], v[66:67], v[132:133] op_sel_hi:[1,0] neg_lo:[0,1] neg_hi:[0,1]
	v_pk_mul_f32 v[66:67], v[66:67], v[132:133] op_sel:[0,1]
	v_pk_fma_f32 v[66:67], v[194:195], v[66:67], v[210:211]
	v_pk_add_f32 v[68:69], v[68:69], v[132:133] op_sel_hi:[1,0] neg_lo:[0,1] neg_hi:[0,1]
	v_pk_mul_f32 v[68:69], v[68:69], v[132:133] op_sel:[0,1]
	v_pk_fma_f32 v[68:69], v[196:197], v[68:69], v[212:213]
	v_pk_add_f32 v[70:71], v[70:71], v[132:133] op_sel_hi:[1,0] neg_lo:[0,1] neg_hi:[0,1]
	v_pk_mul_f32 v[70:71], v[70:71], v[132:133] op_sel:[0,1]
	v_pk_fma_f32 v[70:71], v[198:199], v[70:71], v[214:215]
	v_pk_add_f32 v[72:73], v[72:73], v[132:133] op_sel_hi:[1,0] neg_lo:[0,1] neg_hi:[0,1]
	v_pk_mul_f32 v[72:73], v[72:73], v[132:133] op_sel:[0,1]
	v_pk_fma_f32 v[72:73], v[200:201], v[72:73], v[216:217]
	v_cvt_pk_bf16_f32 v66, v66, v67
	v_cvt_pk_bf16_f32 v67, v68, v69
	v_cvt_pk_bf16_f32 v68, v70, v71
	v_cvt_pk_bf16_f32 v69, v72, v73
	global_store_dwordx4 v[154:155], v[66:69], off
	s_mov_b32 s70, 0x10100
	s_mov_b32 s71, 0
	v_lshl_add_u64 v[156:157], v[222:223], 0, s[70:71]
	v_pk_add_f32 v[74:75], v[74:75], v[134:135] op_sel_hi:[1,0] neg_lo:[0,1] neg_hi:[0,1]
	v_pk_mul_f32 v[74:75], v[74:75], v[134:135] op_sel:[0,1]
	v_pk_fma_f32 v[74:75], v[194:195], v[74:75], v[210:211]
	v_pk_add_f32 v[76:77], v[76:77], v[134:135] op_sel_hi:[1,0] neg_lo:[0,1] neg_hi:[0,1]
	v_pk_mul_f32 v[76:77], v[76:77], v[134:135] op_sel:[0,1]
	v_pk_fma_f32 v[76:77], v[196:197], v[76:77], v[212:213]
	v_pk_add_f32 v[78:79], v[78:79], v[134:135] op_sel_hi:[1,0] neg_lo:[0,1] neg_hi:[0,1]
	v_pk_mul_f32 v[78:79], v[78:79], v[134:135] op_sel:[0,1]
	v_pk_fma_f32 v[78:79], v[198:199], v[78:79], v[214:215]
	v_pk_add_f32 v[80:81], v[80:81], v[134:135] op_sel_hi:[1,0] neg_lo:[0,1] neg_hi:[0,1]
	v_pk_mul_f32 v[80:81], v[80:81], v[134:135] op_sel:[0,1]
	v_pk_fma_f32 v[80:81], v[200:201], v[80:81], v[216:217]
	v_cvt_pk_bf16_f32 v74, v74, v75
	v_cvt_pk_bf16_f32 v75, v76, v77
	v_cvt_pk_bf16_f32 v76, v78, v79
	v_cvt_pk_bf16_f32 v77, v80, v81
	global_store_dwordx4 v[156:157], v[74:77], off
	s_mov_b32 s70, 0x20100
	s_mov_b32 s71, 0
	v_lshl_add_u64 v[154:155], v[222:223], 0, s[70:71]
	v_pk_add_f32 v[82:83], v[82:83], v[136:137] op_sel_hi:[1,0] neg_lo:[0,1] neg_hi:[0,1]
	v_pk_mul_f32 v[82:83], v[82:83], v[136:137] op_sel:[0,1]
	v_pk_fma_f32 v[82:83], v[194:195], v[82:83], v[210:211]
	v_pk_add_f32 v[84:85], v[84:85], v[136:137] op_sel_hi:[1,0] neg_lo:[0,1] neg_hi:[0,1]
	v_pk_mul_f32 v[84:85], v[84:85], v[136:137] op_sel:[0,1]
	v_pk_fma_f32 v[84:85], v[196:197], v[84:85], v[212:213]
	v_pk_add_f32 v[86:87], v[86:87], v[136:137] op_sel_hi:[1,0] neg_lo:[0,1] neg_hi:[0,1]
	v_pk_mul_f32 v[86:87], v[86:87], v[136:137] op_sel:[0,1]
	v_pk_fma_f32 v[86:87], v[198:199], v[86:87], v[214:215]
	v_pk_add_f32 v[88:89], v[88:89], v[136:137] op_sel_hi:[1,0] neg_lo:[0,1] neg_hi:[0,1]
	v_pk_mul_f32 v[88:89], v[88:89], v[136:137] op_sel:[0,1]
	v_pk_fma_f32 v[88:89], v[200:201], v[88:89], v[216:217]
	v_cvt_pk_bf16_f32 v82, v82, v83
	v_cvt_pk_bf16_f32 v83, v84, v85
	v_cvt_pk_bf16_f32 v84, v86, v87
	v_cvt_pk_bf16_f32 v85, v88, v89
	global_store_dwordx4 v[154:155], v[82:85], off
	s_mov_b32 s70, 0x30100
	s_mov_b32 s71, 0
	v_lshl_add_u64 v[156:157], v[222:223], 0, s[70:71]
	v_pk_add_f32 v[90:91], v[90:91], v[138:139] op_sel_hi:[1,0] neg_lo:[0,1] neg_hi:[0,1]
	v_pk_mul_f32 v[90:91], v[90:91], v[138:139] op_sel:[0,1]
	v_pk_fma_f32 v[90:91], v[194:195], v[90:91], v[210:211]
	v_pk_add_f32 v[92:93], v[92:93], v[138:139] op_sel_hi:[1,0] neg_lo:[0,1] neg_hi:[0,1]
	v_pk_mul_f32 v[92:93], v[92:93], v[138:139] op_sel:[0,1]
	v_pk_fma_f32 v[92:93], v[196:197], v[92:93], v[212:213]
	v_pk_add_f32 v[94:95], v[94:95], v[138:139] op_sel_hi:[1,0] neg_lo:[0,1] neg_hi:[0,1]
	v_pk_mul_f32 v[94:95], v[94:95], v[138:139] op_sel:[0,1]
	v_pk_fma_f32 v[94:95], v[198:199], v[94:95], v[214:215]
	v_pk_add_f32 v[96:97], v[96:97], v[138:139] op_sel_hi:[1,0] neg_lo:[0,1] neg_hi:[0,1]
	v_pk_mul_f32 v[96:97], v[96:97], v[138:139] op_sel:[0,1]
	v_pk_fma_f32 v[96:97], v[200:201], v[96:97], v[216:217]
	v_cvt_pk_bf16_f32 v90, v90, v91
	v_cvt_pk_bf16_f32 v91, v92, v93
	v_cvt_pk_bf16_f32 v92, v94, v95
	v_cvt_pk_bf16_f32 v93, v96, v97
	global_store_dwordx4 v[156:157], v[90:93], off
	s_mov_b32 s70, 0x40000
	s_mov_b32 s71, 0
	v_lshl_add_u64 v[154:155], v[222:223], 0, s[70:71]
	v_pk_add_f32 v[34:35], v[34:35], v[232:233] op_sel_hi:[1,0] neg_lo:[0,1] neg_hi:[0,1]
	v_pk_mul_f32 v[34:35], v[34:35], v[232:233] op_sel:[0,1]
	v_pk_fma_f32 v[34:35], v[186:187], v[34:35], v[202:203]
	v_pk_add_f32 v[36:37], v[36:37], v[232:233] op_sel_hi:[1,0] neg_lo:[0,1] neg_hi:[0,1]
	v_pk_mul_f32 v[36:37], v[36:37], v[232:233] op_sel:[0,1]
	v_pk_fma_f32 v[36:37], v[188:189], v[36:37], v[204:205]
	v_pk_add_f32 v[38:39], v[38:39], v[232:233] op_sel_hi:[1,0] neg_lo:[0,1] neg_hi:[0,1]
	v_pk_mul_f32 v[38:39], v[38:39], v[232:233] op_sel:[0,1]
	v_pk_fma_f32 v[38:39], v[190:191], v[38:39], v[206:207]
	v_pk_add_f32 v[40:41], v[40:41], v[232:233] op_sel_hi:[1,0] neg_lo:[0,1] neg_hi:[0,1]
	v_pk_mul_f32 v[40:41], v[40:41], v[232:233] op_sel:[0,1]
	v_pk_fma_f32 v[40:41], v[192:193], v[40:41], v[208:209]
	v_cvt_pk_bf16_f32 v34, v34, v35
	v_cvt_pk_bf16_f32 v35, v36, v37
	v_cvt_pk_bf16_f32 v36, v38, v39
	v_cvt_pk_bf16_f32 v37, v40, v41
	global_store_dwordx4 v[154:155], v[34:37], off
	s_mov_b32 s70, 0x50000
	s_mov_b32 s71, 0
	v_lshl_add_u64 v[156:157], v[222:223], 0, s[70:71]
	v_pk_add_f32 v[42:43], v[42:43], v[234:235] op_sel_hi:[1,0] neg_lo:[0,1] neg_hi:[0,1]
	v_pk_mul_f32 v[42:43], v[42:43], v[234:235] op_sel:[0,1]
	v_pk_fma_f32 v[42:43], v[186:187], v[42:43], v[202:203]
	v_pk_add_f32 v[44:45], v[44:45], v[234:235] op_sel_hi:[1,0] neg_lo:[0,1] neg_hi:[0,1]
	v_pk_mul_f32 v[44:45], v[44:45], v[234:235] op_sel:[0,1]
	v_pk_fma_f32 v[44:45], v[188:189], v[44:45], v[204:205]
	v_pk_add_f32 v[46:47], v[46:47], v[234:235] op_sel_hi:[1,0] neg_lo:[0,1] neg_hi:[0,1]
	v_pk_mul_f32 v[46:47], v[46:47], v[234:235] op_sel:[0,1]
	v_pk_fma_f32 v[46:47], v[190:191], v[46:47], v[206:207]
	v_pk_add_f32 v[48:49], v[48:49], v[234:235] op_sel_hi:[1,0] neg_lo:[0,1] neg_hi:[0,1]
	v_pk_mul_f32 v[48:49], v[48:49], v[234:235] op_sel:[0,1]
	v_pk_fma_f32 v[48:49], v[192:193], v[48:49], v[208:209]
	v_cvt_pk_bf16_f32 v42, v42, v43
	v_cvt_pk_bf16_f32 v43, v44, v45
	v_cvt_pk_bf16_f32 v44, v46, v47
	v_cvt_pk_bf16_f32 v45, v48, v49
	global_store_dwordx4 v[156:157], v[42:45], off
	s_mov_b32 s70, 0x60000
	s_mov_b32 s71, 0
	v_lshl_add_u64 v[154:155], v[222:223], 0, s[70:71]
	v_pk_add_f32 v[50:51], v[50:51], v[236:237] op_sel_hi:[1,0] neg_lo:[0,1] neg_hi:[0,1]
	v_pk_mul_f32 v[50:51], v[50:51], v[236:237] op_sel:[0,1]
	v_pk_fma_f32 v[50:51], v[186:187], v[50:51], v[202:203]
	v_pk_add_f32 v[52:53], v[52:53], v[236:237] op_sel_hi:[1,0] neg_lo:[0,1] neg_hi:[0,1]
	v_pk_mul_f32 v[52:53], v[52:53], v[236:237] op_sel:[0,1]
	v_pk_fma_f32 v[52:53], v[188:189], v[52:53], v[204:205]
	v_pk_add_f32 v[54:55], v[54:55], v[236:237] op_sel_hi:[1,0] neg_lo:[0,1] neg_hi:[0,1]
	v_pk_mul_f32 v[54:55], v[54:55], v[236:237] op_sel:[0,1]
	v_pk_fma_f32 v[54:55], v[190:191], v[54:55], v[206:207]
	v_pk_add_f32 v[56:57], v[56:57], v[236:237] op_sel_hi:[1,0] neg_lo:[0,1] neg_hi:[0,1]
	v_pk_mul_f32 v[56:57], v[56:57], v[236:237] op_sel:[0,1]
	v_pk_fma_f32 v[56:57], v[192:193], v[56:57], v[208:209]
	v_cvt_pk_bf16_f32 v50, v50, v51
	v_cvt_pk_bf16_f32 v51, v52, v53
	v_cvt_pk_bf16_f32 v52, v54, v55
	v_cvt_pk_bf16_f32 v53, v56, v57
	global_store_dwordx4 v[154:155], v[50:53], off
	s_mov_b32 s70, 0x70000
	s_mov_b32 s71, 0
	v_lshl_add_u64 v[156:157], v[222:223], 0, s[70:71]
	v_pk_add_f32 v[58:59], v[58:59], v[150:151] op_sel_hi:[1,0] neg_lo:[0,1] neg_hi:[0,1]
	v_pk_mul_f32 v[58:59], v[58:59], v[150:151] op_sel:[0,1]
	v_pk_fma_f32 v[58:59], v[186:187], v[58:59], v[202:203]
	v_pk_add_f32 v[60:61], v[60:61], v[150:151] op_sel_hi:[1,0] neg_lo:[0,1] neg_hi:[0,1]
	v_pk_mul_f32 v[60:61], v[60:61], v[150:151] op_sel:[0,1]
	v_pk_fma_f32 v[60:61], v[188:189], v[60:61], v[204:205]
	v_pk_add_f32 v[62:63], v[62:63], v[150:151] op_sel_hi:[1,0] neg_lo:[0,1] neg_hi:[0,1]
	v_pk_mul_f32 v[62:63], v[62:63], v[150:151] op_sel:[0,1]
	v_pk_fma_f32 v[62:63], v[190:191], v[62:63], v[206:207]
	v_pk_add_f32 v[64:65], v[64:65], v[150:151] op_sel_hi:[1,0] neg_lo:[0,1] neg_hi:[0,1]
	v_pk_mul_f32 v[64:65], v[64:65], v[150:151] op_sel:[0,1]
	v_pk_fma_f32 v[64:65], v[192:193], v[64:65], v[208:209]
	v_cvt_pk_bf16_f32 v58, v58, v59
	v_cvt_pk_bf16_f32 v59, v60, v61
	v_cvt_pk_bf16_f32 v60, v62, v63
	v_cvt_pk_bf16_f32 v61, v64, v65
	global_store_dwordx4 v[156:157], v[58:61], off
	s_mov_b32 s70, 0x40100
	s_mov_b32 s71, 0
	v_lshl_add_u64 v[154:155], v[222:223], 0, s[70:71]
	v_pk_add_f32 v[2:3], v[2:3], v[232:233] op_sel_hi:[1,0] neg_lo:[0,1] neg_hi:[0,1]
	v_pk_mul_f32 v[2:3], v[2:3], v[232:233] op_sel:[0,1]
	v_pk_fma_f32 v[2:3], v[194:195], v[2:3], v[210:211]
	v_pk_add_f32 v[4:5], v[4:5], v[232:233] op_sel_hi:[1,0] neg_lo:[0,1] neg_hi:[0,1]
	v_pk_mul_f32 v[4:5], v[4:5], v[232:233] op_sel:[0,1]
	v_pk_fma_f32 v[4:5], v[196:197], v[4:5], v[212:213]
	v_pk_add_f32 v[6:7], v[6:7], v[232:233] op_sel_hi:[1,0] neg_lo:[0,1] neg_hi:[0,1]
	v_pk_mul_f32 v[6:7], v[6:7], v[232:233] op_sel:[0,1]
	v_pk_fma_f32 v[6:7], v[198:199], v[6:7], v[214:215]
	v_pk_add_f32 v[8:9], v[8:9], v[232:233] op_sel_hi:[1,0] neg_lo:[0,1] neg_hi:[0,1]
	v_pk_mul_f32 v[8:9], v[8:9], v[232:233] op_sel:[0,1]
	v_pk_fma_f32 v[8:9], v[200:201], v[8:9], v[216:217]
	v_cvt_pk_bf16_f32 v2, v2, v3
	v_cvt_pk_bf16_f32 v3, v4, v5
	v_cvt_pk_bf16_f32 v4, v6, v7
	v_cvt_pk_bf16_f32 v5, v8, v9
	global_store_dwordx4 v[154:155], v[2:5], off
	s_mov_b32 s70, 0x50100
	s_mov_b32 s71, 0
	v_lshl_add_u64 v[156:157], v[222:223], 0, s[70:71]
	v_pk_add_f32 v[10:11], v[10:11], v[234:235] op_sel_hi:[1,0] neg_lo:[0,1] neg_hi:[0,1]
	v_pk_mul_f32 v[10:11], v[10:11], v[234:235] op_sel:[0,1]
	v_pk_fma_f32 v[10:11], v[194:195], v[10:11], v[210:211]
	v_pk_add_f32 v[12:13], v[12:13], v[234:235] op_sel_hi:[1,0] neg_lo:[0,1] neg_hi:[0,1]
	v_pk_mul_f32 v[12:13], v[12:13], v[234:235] op_sel:[0,1]
	v_pk_fma_f32 v[12:13], v[196:197], v[12:13], v[212:213]
	v_pk_add_f32 v[14:15], v[14:15], v[234:235] op_sel_hi:[1,0] neg_lo:[0,1] neg_hi:[0,1]
	v_pk_mul_f32 v[14:15], v[14:15], v[234:235] op_sel:[0,1]
	v_pk_fma_f32 v[14:15], v[198:199], v[14:15], v[214:215]
	v_pk_add_f32 v[16:17], v[16:17], v[234:235] op_sel_hi:[1,0] neg_lo:[0,1] neg_hi:[0,1]
	v_pk_mul_f32 v[16:17], v[16:17], v[234:235] op_sel:[0,1]
	v_pk_fma_f32 v[16:17], v[200:201], v[16:17], v[216:217]
	v_cvt_pk_bf16_f32 v10, v10, v11
	v_cvt_pk_bf16_f32 v11, v12, v13
	v_cvt_pk_bf16_f32 v12, v14, v15
	v_cvt_pk_bf16_f32 v13, v16, v17
	global_store_dwordx4 v[156:157], v[10:13], off
	s_mov_b32 s70, 0x60100
	s_mov_b32 s71, 0
	v_lshl_add_u64 v[154:155], v[222:223], 0, s[70:71]
	v_pk_add_f32 v[18:19], v[18:19], v[236:237] op_sel_hi:[1,0] neg_lo:[0,1] neg_hi:[0,1]
	v_pk_mul_f32 v[18:19], v[18:19], v[236:237] op_sel:[0,1]
	v_pk_fma_f32 v[18:19], v[194:195], v[18:19], v[210:211]
	v_pk_add_f32 v[20:21], v[20:21], v[236:237] op_sel_hi:[1,0] neg_lo:[0,1] neg_hi:[0,1]
	v_pk_mul_f32 v[20:21], v[20:21], v[236:237] op_sel:[0,1]
	v_pk_fma_f32 v[20:21], v[196:197], v[20:21], v[212:213]
	v_pk_add_f32 v[22:23], v[22:23], v[236:237] op_sel_hi:[1,0] neg_lo:[0,1] neg_hi:[0,1]
	v_pk_mul_f32 v[22:23], v[22:23], v[236:237] op_sel:[0,1]
	v_pk_fma_f32 v[22:23], v[198:199], v[22:23], v[214:215]
	v_pk_add_f32 v[24:25], v[24:25], v[236:237] op_sel_hi:[1,0] neg_lo:[0,1] neg_hi:[0,1]
	v_pk_mul_f32 v[24:25], v[24:25], v[236:237] op_sel:[0,1]
	v_pk_fma_f32 v[24:25], v[200:201], v[24:25], v[216:217]
	v_cvt_pk_bf16_f32 v18, v18, v19
	v_cvt_pk_bf16_f32 v19, v20, v21
	v_cvt_pk_bf16_f32 v20, v22, v23
	v_cvt_pk_bf16_f32 v21, v24, v25
	global_store_dwordx4 v[154:155], v[18:21], off
	s_mov_b32 s70, 0x70100
	s_mov_b32 s71, 0
	v_lshl_add_u64 v[156:157], v[222:223], 0, s[70:71]
	v_pk_add_f32 v[26:27], v[26:27], v[150:151] op_sel_hi:[1,0] neg_lo:[0,1] neg_hi:[0,1]
	v_pk_mul_f32 v[26:27], v[26:27], v[150:151] op_sel:[0,1]
	v_pk_fma_f32 v[26:27], v[194:195], v[26:27], v[210:211]
	v_pk_add_f32 v[28:29], v[28:29], v[150:151] op_sel_hi:[1,0] neg_lo:[0,1] neg_hi:[0,1]
	v_pk_mul_f32 v[28:29], v[28:29], v[150:151] op_sel:[0,1]
	v_pk_fma_f32 v[28:29], v[196:197], v[28:29], v[212:213]
	v_pk_add_f32 v[30:31], v[30:31], v[150:151] op_sel_hi:[1,0] neg_lo:[0,1] neg_hi:[0,1]
	v_pk_mul_f32 v[30:31], v[30:31], v[150:151] op_sel:[0,1]
	v_pk_fma_f32 v[30:31], v[198:199], v[30:31], v[214:215]
	v_pk_add_f32 v[32:33], v[32:33], v[150:151] op_sel_hi:[1,0] neg_lo:[0,1] neg_hi:[0,1]
	v_pk_mul_f32 v[32:33], v[32:33], v[150:151] op_sel:[0,1]
	v_pk_fma_f32 v[32:33], v[200:201], v[32:33], v[216:217]
	v_cvt_pk_bf16_f32 v26, v26, v27
	v_cvt_pk_bf16_f32 v27, v28, v29
	v_cvt_pk_bf16_f32 v28, v30, v31
	v_cvt_pk_bf16_f32 v29, v32, v33
	global_store_dwordx4 v[156:157], v[26:29], off
	s_waitcnt lgkmcnt(0)
	s_barrier
	s_branch .LBB0_1032

.LBB0_1051:
	s_waitcnt vmcnt(0)
	s_waitcnt vmcnt(0)
	s_barrier
	s_mov_b64 s[0:1], exec
	v_readlane_b32 s2, v253, 53
	v_readlane_b32 s3, v253, 54
	v_readlane_b32 s44, v254, 47
	v_readlane_b32 s38, v254, 42
	v_readlane_b32 s42, v254, 14
	v_readlane_b32 s64, v254, 20
	s_and_b64 s[2:3], s[0:1], s[2:3]
	v_readlane_b32 s45, v254, 48
	v_readlane_b32 s39, v254, 43
	v_readlane_b32 s43, v254, 15
	v_readlane_b32 s65, v254, 21
	s_mov_b64 exec, s[2:3]
	s_branch .LBB0_1103
	s_add_i32 s2, 0, 0x20000
	s_mov_b32 s10, s93
	v_mov_b32_e32 v1, s2
	s_waitcnt vmcnt(0) expcnt(0) lgkmcnt(0)
	ds_read_b32 v3, v1
	s_add_i32 s2, 0, 0x20004
	v_mov_b32_e32 v1, s2
	ds_read_b32 v2, v1
	s_waitcnt lgkmcnt(1)
	v_cmp_ne_u32_e32 vcc, 0, v3
	s_cbranch_vccnz .LBB0_1067
	s_mov_b32 s11, 1
	v_mov_b32_e32 v17, 0
	s_branch .LBB0_1055

.LBB0_1106:
.LBB0_1114:
	s_waitcnt vmcnt(0)
	s_barrier
	s_mov_b64 s[0:1], exec
	v_readlane_b32 s2, v253, 53
	v_readlane_b32 s3, v253, 54
	s_and_b64 s[2:3], s[0:1], s[2:3]
	s_mov_b64 exec, s[2:3]
	s_cbranch_execz .LBB0_1166
	s_add_i32 s2, 0, 0x20000
	s_mov_b32 s12, s93
	v_mov_b32_e32 v1, s2
	s_waitcnt vmcnt(0) expcnt(0) lgkmcnt(0)
	ds_read_b32 v3, v1
	s_add_i32 s2, 0, 0x20004
	v_mov_b32_e32 v1, s2
	ds_read_b32 v2, v1
	s_waitcnt lgkmcnt(1)
	v_cmp_ne_u32_e32 vcc, 0, v3
	s_cbranch_vccnz .LBB0_1130
	s_mov_b32 s13, 1
	v_mov_b32_e32 v17, 0
	s_branch .LBB0_1118

.Lp9_poll:
	global_load_dword v240, v238, s[44:45] sc1
	s_waitcnt vmcnt(0)
	v_readfirstlane_b32 s98, v240
	s_nop 3
	s_cmp_ge_u32 s98, 8
	s_cbranch_scc1 .Lp9_polled
	s_sleep 1
	s_add_i32 s99, s99, 1
	s_cmp_lt_u32 s99, 0x4000
	s_cbranch_scc1 .Lp9_poll

.LBB0_1595:
	v_add_u32_e32 v2, s1, v168
	v_ashrrev_i32_e32 v3, 31, v2
	v_add_u32_e32 v4, 16, v2
	v_lshlrev_b64 v[2:3], 11, v[2:3]
	v_ashrrev_i32_e32 v5, 31, v4
	v_lshl_add_u64 v[2:3], v[156:157], 0, v[2:3]
	v_lshlrev_b64 v[6:7], 11, v[4:5]
	global_load_dwordx4 v[2:5], v[2:3], off
	v_lshl_add_u64 v[6:7], v[156:157], 0, v[6:7]
	global_load_dwordx4 v[114:117], v[6:7], off
	s_add_i32 s1, s1, 32
	s_cmpk_eq_i32 s1, 0x80
	s_waitcnt vmcnt(1)
	v_mfma_f32_32x32x16_bf16 v[176:191], v[2:5], v[130:133], 0
	v_mfma_f32_32x32x16_bf16 v[192:207], v[2:5], v[134:137], 0
	v_mfma_f32_32x32x16_bf16 v[208:223], v[2:5], v[138:141], 0
	v_mfma_f32_32x32x16_bf16 v[224:239], v[2:5], v[142:145], 0
	s_waitcnt vmcnt(0)
	v_mfma_f32_32x32x16_bf16 v[50:65], v[114:117], v[130:133], 0
	v_mfma_f32_32x32x16_bf16 v[66:81], v[114:117], v[134:137], 0
	v_mfma_f32_32x32x16_bf16 v[82:97], v[114:117], v[138:141], 0
	v_mfma_f32_32x32x16_bf16 v[98:113], v[114:117], v[142:145], 0
	s_nop 7
	v_fma_f32 v244, -v153, v35, v176
	v_fma_f32 v245, v153, v34, v192
	v_fma_f32 v246, -v155, v119, v208
	v_fma_f32 v247, v155, v118, v224
	v_fma_f32 v240, v152, v34, v244
	v_fma_f32 v241, v152, v35, v245
	v_fma_f32 v242, v154, v118, v246
	v_fma_f32 v243, v154, v119, v247
	v_fma_f32 v244, -v153, v241, v177
	v_fma_f32 v245, v153, v240, v193
	v_fma_f32 v246, -v155, v243, v209
	v_fma_f32 v247, v155, v242, v225
	v_fma_f32 v34, v152, v240, v244
	v_fma_f32 v35, v152, v241, v245
	v_fma_f32 v118, v154, v242, v246
	v_fma_f32 v119, v154, v243, v247
	v_fma_f32 v244, -v153, v35, v178
	v_fma_f32 v245, v153, v34, v194
	v_fma_f32 v246, -v155, v119, v210
	v_fma_f32 v247, v155, v118, v226
	v_fma_f32 v240, v152, v34, v244
	v_fma_f32 v241, v152, v35, v245
	v_fma_f32 v242, v154, v118, v246
	v_fma_f32 v243, v154, v119, v247
	v_fma_f32 v244, -v153, v241, v179
	v_fma_f32 v245, v153, v240, v195
	v_fma_f32 v246, -v155, v243, v211
	v_fma_f32 v247, v155, v242, v227
	v_fma_f32 v34, v152, v240, v244
	v_fma_f32 v35, v152, v241, v245
	v_fma_f32 v118, v154, v242, v246
	v_fma_f32 v119, v154, v243, v247
	v_fma_f32 v244, -v153, v35, v180
	v_fma_f32 v245, v153, v34, v196
	v_fma_f32 v246, -v155, v119, v212
	v_fma_f32 v247, v155, v118, v228
	v_fma_f32 v240, v152, v34, v244
	v_fma_f32 v241, v152, v35, v245
	v_fma_f32 v242, v154, v118, v246
	v_fma_f32 v243, v154, v119, v247
	v_fma_f32 v244, -v153, v241, v181
	v_fma_f32 v245, v153, v240, v197
	v_fma_f32 v246, -v155, v243, v213
	v_fma_f32 v247, v155, v242, v229
	v_fma_f32 v34, v152, v240, v244
	v_fma_f32 v35, v152, v241, v245
	v_fma_f32 v118, v154, v242, v246
	v_fma_f32 v119, v154, v243, v247
	v_fma_f32 v244, -v153, v35, v182
	v_fma_f32 v245, v153, v34, v198
	v_fma_f32 v246, -v155, v119, v214
	v_fma_f32 v247, v155, v118, v230
	v_fma_f32 v240, v152, v34, v244
	v_fma_f32 v241, v152, v35, v245
	v_fma_f32 v242, v154, v118, v246
	v_fma_f32 v243, v154, v119, v247
	v_fma_f32 v244, -v153, v241, v183
	v_fma_f32 v245, v153, v240, v199
	v_fma_f32 v246, -v155, v243, v215
	v_fma_f32 v247, v155, v242, v231
	v_fma_f32 v34, v152, v240, v244
	v_fma_f32 v35, v152, v241, v245
	v_fma_f32 v118, v154, v242, v246
	v_fma_f32 v119, v154, v243, v247
	v_fma_f32 v244, -v153, v35, v184
	v_fma_f32 v245, v153, v34, v200
	v_fma_f32 v246, -v155, v119, v216
	v_fma_f32 v247, v155, v118, v232
	v_fma_f32 v240, v152, v34, v244
	v_fma_f32 v241, v152, v35, v245
	v_fma_f32 v242, v154, v118, v246
	v_fma_f32 v243, v154, v119, v247
	v_fma_f32 v244, -v153, v241, v185
	v_fma_f32 v245, v153, v240, v201
	v_fma_f32 v246, -v155, v243, v217
	v_fma_f32 v247, v155, v242, v233
	v_fma_f32 v34, v152, v240, v244
	v_fma_f32 v35, v152, v241, v245
	v_fma_f32 v118, v154, v242, v246
	v_fma_f32 v119, v154, v243, v247
	v_fma_f32 v244, -v153, v35, v186
	v_fma_f32 v245, v153, v34, v202
	v_fma_f32 v246, -v155, v119, v218
	v_fma_f32 v247, v155, v118, v234
	v_fma_f32 v240, v152, v34, v244
	v_fma_f32 v241, v152, v35, v245
	v_fma_f32 v242, v154, v118, v246
	v_fma_f32 v243, v154, v119, v247
	v_fma_f32 v244, -v153, v241, v187
	v_fma_f32 v245, v153, v240, v203
	v_fma_f32 v246, -v155, v243, v219
	v_fma_f32 v247, v155, v242, v235
	v_fma_f32 v34, v152, v240, v244
	v_fma_f32 v35, v152, v241, v245
	v_fma_f32 v118, v154, v242, v246
	v_fma_f32 v119, v154, v243, v247
	v_fma_f32 v244, -v153, v35, v188
	v_fma_f32 v245, v153, v34, v204
	v_fma_f32 v246, -v155, v119, v220
	v_fma_f32 v247, v155, v118, v236
	v_fma_f32 v240, v152, v34, v244
	v_fma_f32 v241, v152, v35, v245
	v_fma_f32 v242, v154, v118, v246
	v_fma_f32 v243, v154, v119, v247
	v_fma_f32 v244, -v153, v241, v189
	v_fma_f32 v245, v153, v240, v205
	v_fma_f32 v246, -v155, v243, v221
	v_fma_f32 v247, v155, v242, v237
	v_fma_f32 v34, v152, v240, v244
	v_fma_f32 v35, v152, v241, v245
	v_fma_f32 v118, v154, v242, v246
	v_fma_f32 v119, v154, v243, v247
	v_fma_f32 v244, -v153, v35, v190
	v_fma_f32 v245, v153, v34, v206
	v_fma_f32 v246, -v155, v119, v222
	v_fma_f32 v247, v155, v118, v238
	v_fma_f32 v240, v152, v34, v244
	v_fma_f32 v241, v152, v35, v245
	v_fma_f32 v242, v154, v118, v246
	v_fma_f32 v243, v154, v119, v247
	v_fma_f32 v244, -v153, v241, v191
	v_fma_f32 v245, v153, v240, v207
	v_fma_f32 v246, -v155, v243, v223
	v_fma_f32 v247, v155, v242, v239
	v_fma_f32 v34, v152, v240, v244
	v_fma_f32 v35, v152, v241, v245
	v_fma_f32 v118, v154, v242, v246
	v_fma_f32 v119, v154, v243, v247
	v_fma_f32 v244, -v153, v35, v50
	v_fma_f32 v245, v153, v34, v66
	v_fma_f32 v246, -v155, v119, v82
	v_fma_f32 v247, v155, v118, v98
	v_fma_f32 v240, v152, v34, v244
	v_fma_f32 v241, v152, v35, v245
	v_fma_f32 v242, v154, v118, v246
	v_fma_f32 v243, v154, v119, v247
	v_fma_f32 v244, -v153, v241, v51
	v_fma_f32 v245, v153, v240, v67
	v_fma_f32 v246, -v155, v243, v83
	v_fma_f32 v247, v155, v242, v99
	v_fma_f32 v34, v152, v240, v244
	v_fma_f32 v35, v152, v241, v245
	v_fma_f32 v118, v154, v242, v246
	v_fma_f32 v119, v154, v243, v247
	v_fma_f32 v244, -v153, v35, v52
	v_fma_f32 v245, v153, v34, v68
	v_fma_f32 v246, -v155, v119, v84
	v_fma_f32 v247, v155, v118, v100
	v_fma_f32 v240, v152, v34, v244
	v_fma_f32 v241, v152, v35, v245
	v_fma_f32 v242, v154, v118, v246
	v_fma_f32 v243, v154, v119, v247
	v_fma_f32 v244, -v153, v241, v53
	v_fma_f32 v245, v153, v240, v69
	v_fma_f32 v246, -v155, v243, v85
	v_fma_f32 v247, v155, v242, v101
	v_fma_f32 v34, v152, v240, v244
	v_fma_f32 v35, v152, v241, v245
	v_fma_f32 v118, v154, v242, v246
	v_fma_f32 v119, v154, v243, v247
	v_fma_f32 v244, -v153, v35, v54
	v_fma_f32 v245, v153, v34, v70
	v_fma_f32 v246, -v155, v119, v86
	v_fma_f32 v247, v155, v118, v102
	v_fma_f32 v240, v152, v34, v244
	v_fma_f32 v241, v152, v35, v245
	v_fma_f32 v242, v154, v118, v246
	v_fma_f32 v243, v154, v119, v247
	v_fma_f32 v244, -v153, v241, v55
	v_fma_f32 v245, v153, v240, v71
	v_fma_f32 v246, -v155, v243, v87
	v_fma_f32 v247, v155, v242, v103
	v_fma_f32 v34, v152, v240, v244
	v_fma_f32 v35, v152, v241, v245
	v_fma_f32 v118, v154, v242, v246
	v_fma_f32 v119, v154, v243, v247
	v_fma_f32 v244, -v153, v35, v56
	v_fma_f32 v245, v153, v34, v72
	v_fma_f32 v246, -v155, v119, v88
	v_fma_f32 v247, v155, v118, v104
	v_fma_f32 v240, v152, v34, v244
	v_fma_f32 v241, v152, v35, v245
	v_fma_f32 v242, v154, v118, v246
	v_fma_f32 v243, v154, v119, v247
	v_fma_f32 v244, -v153, v241, v57
	v_fma_f32 v245, v153, v240, v73
	v_fma_f32 v246, -v155, v243, v89
	v_fma_f32 v247, v155, v242, v105
	v_fma_f32 v34, v152, v240, v244
	v_fma_f32 v35, v152, v241, v245
	v_fma_f32 v118, v154, v242, v246
	v_fma_f32 v119, v154, v243, v247
	v_fma_f32 v244, -v153, v35, v58
	v_fma_f32 v245, v153, v34, v74
	v_fma_f32 v246, -v155, v119, v90
	v_fma_f32 v247, v155, v118, v106
	v_fma_f32 v240, v152, v34, v244
	v_fma_f32 v241, v152, v35, v245
	v_fma_f32 v242, v154, v118, v246
	v_fma_f32 v243, v154, v119, v247
	v_fma_f32 v244, -v153, v241, v59
	v_fma_f32 v245, v153, v240, v75
	v_fma_f32 v246, -v155, v243, v91
	v_fma_f32 v247, v155, v242, v107
	v_fma_f32 v34, v152, v240, v244
	v_fma_f32 v35, v152, v241, v245
	v_fma_f32 v118, v154, v242, v246
	v_fma_f32 v119, v154, v243, v247
	v_fma_f32 v244, -v153, v35, v60
	v_fma_f32 v245, v153, v34, v76
	v_fma_f32 v246, -v155, v119, v92
	v_fma_f32 v247, v155, v118, v108
	v_fma_f32 v240, v152, v34, v244
	v_fma_f32 v241, v152, v35, v245
	v_fma_f32 v242, v154, v118, v246
	v_fma_f32 v243, v154, v119, v247
	v_fma_f32 v244, -v153, v241, v61
	v_fma_f32 v245, v153, v240, v77
	v_fma_f32 v246, -v155, v243, v93
	v_fma_f32 v247, v155, v242, v109
	v_fma_f32 v34, v152, v240, v244
	v_fma_f32 v35, v152, v241, v245
	v_fma_f32 v118, v154, v242, v246
	v_fma_f32 v119, v154, v243, v247
	v_fma_f32 v244, -v153, v35, v62
	v_fma_f32 v245, v153, v34, v78
	v_fma_f32 v246, -v155, v119, v94
	v_fma_f32 v247, v155, v118, v110
	v_fma_f32 v240, v152, v34, v244
	v_fma_f32 v241, v152, v35, v245
	v_fma_f32 v242, v154, v118, v246
	v_fma_f32 v243, v154, v119, v247
	v_fma_f32 v244, -v153, v241, v63
	v_fma_f32 v245, v153, v240, v79
	v_fma_f32 v246, -v155, v243, v95
	v_fma_f32 v247, v155, v242, v111
	v_fma_f32 v34, v152, v240, v244
	v_fma_f32 v35, v152, v241, v245
	v_fma_f32 v118, v154, v242, v246
	v_fma_f32 v119, v154, v243, v247
	v_fma_f32 v244, -v153, v35, v64
	v_fma_f32 v245, v153, v34, v80
	v_fma_f32 v246, -v155, v119, v96
	v_fma_f32 v247, v155, v118, v112
	v_fma_f32 v240, v152, v34, v244
	v_fma_f32 v241, v152, v35, v245
	v_fma_f32 v242, v154, v118, v246
	v_fma_f32 v243, v154, v119, v247
	v_fma_f32 v244, -v153, v241, v65
	v_fma_f32 v245, v153, v240, v81
	v_fma_f32 v246, -v155, v243, v97
	v_fma_f32 v247, v155, v242, v113
	v_fma_f32 v34, v152, v240, v244
	v_fma_f32 v35, v152, v241, v245
	v_fma_f32 v118, v154, v242, v246
	v_fma_f32 v119, v154, v243, v247
	s_cbranch_scc0 .LBB0_1595
	s_nop 0
	s_nop 0
	s_nop 0
	s_nop 0
	s_nop 0
	s_nop 0
	s_nop 0
	s_nop 0
	s_nop 0
	s_nop 0
	s_nop 0
	s_nop 0
	s_nop 0
	v_lshlrev_b32_e32 v2, 7, v167
	v_or3_b32 v2, v2, v163, v166
	v_ashrrev_i32_e32 v3, 31, v2
	v_lshlrev_b64 v[2:3], 9, v[2:3]
	s_add_i32 s0, s0, s96
	v_lshl_add_u64 v[2:3], v[150:151], 0, v[2:3]
	s_cmpk_gt_i32 s0, 0x1ff
	global_store_dwordx2 v[2:3], v[34:35], off
	global_store_dwordx2 v[2:3], v[118:119], off offset:256
	s_cbranch_scc0 .LBB0_1594
